# LRU: forward pass publishes h_fwd alone (bf16 narrow tile, no silu(ga) re-read/pack); backward pass loads ga + h_fwd narrow tiles and packs with v_perm_b32 before the LDS write
# baseline (speedup 1.0000x reference)
; template <int dir>
; __device__ __forceinline__ void lru_pass(LAS unsigned char* lds, const Params& P, int b, int h, int q, bool dry) {
;     ...
;     bf16_t* Z = (bf16_t*)(P.ws + WS_Z); const bf16_t* ZC = (const bf16_t*)(P.ws + WS_ZC); unsigned* HFW = (unsigned*)(P.ws + WS_HF);
;     const bf16_t* LruW = (const bf16_t*)(P.ws + WS_LRUW);
;     const int cgp = tid & 15, tr = tid >> 4;
;     const int s_i = 16 * ((nl >> 2) & 1) + ((nl >> 3) << 2) + (nl & 3);
;     const bf16_t* Zg = Z + ZSLAB(8 + h, (size_t)b * SEQ) + q * 32;
;     unsigned* Hg = HFW + (size_t)b * SEQ * DM + h * 128 + q * 32;
; __global__ void __launch_bounds__(NTHREADS, 2) fwd_megakernel(Params P) {
;     ...
;         for (int s2 = bx; s2 < 256; s2 += G) { lru_strip(lds, P, ((s2 & 7) << 5) | (s2 >> 3), false); __syncthreads(); }
.LBB0_277:
	s_add_u32 s40, s22, 0x7400000
	s_addc_u32 s41, s23, 0
	s_setprio 0
	s_cmp_lg_u32 s101, 0
	s_cbranch_scc1 .Lpp_b_noy
	s_barrier

; template <int dir>
; __device__ __forceinline__ void lru_pass(LAS unsigned char* lds, const Params& P, int b, int h, int q, bool dry) {
;     const int tid = opaque_tid(), lane = tid & 63, wid = __builtin_amdgcn_readfirstlane(tid >> 6), g = lane >> 5, nl = lane & 31;
;     const int chl = q * 32 + nl, ch = h * 128 + chl;
;     LAS unsigned char* XC = lds;
;     LAS float* AGG = (LAS float*)(lds + 256 * XC_PITCH);
;     LAS unsigned char* WB = lds + 256 * XC_PITCH + 2048;
;     LAS float* CWL = (LAS float*)(lds + 256 * XC_PITCH + 2048 + 64 * XC_PITCH);
;     LAS unsigned char* TIN = lds + LRU_IO_OFF;
;     LAS unsigned char* TOUT = lds + LRU_IO_OFF + 256 * (dir == 0 ? IO_NP : IO_WP);
;     bf16_t* Z = (bf16_t*)(P.ws + WS_Z); const bf16_t* ZC = (const bf16_t*)(P.ws + WS_ZC); unsigned* HFW = (unsigned*)(P.ws + WS_HF);
;     const bf16_t* LruW = (const bf16_t*)(P.ws + WS_LRUW);
;     const int cgp = tid & 15, tr = tid >> 4;
;     const int s_i = 16 * ((nl >> 2) & 1) + ((nl >> 3) << 2) + (nl & 3);
;     const bf16_t* Zg = Z + ZSLAB(8 + h, (size_t)b * SEQ) + q * 32;
;     unsigned* Hg = HFW + (size_t)b * SEQ * DM + h * 128 + q * 32;
;     {
; #pragma unroll
;         for (int i = 0; i < 2; ++i) { const int idx = tid + i * NTHREADS, gate = idx >> 9, n = (idx >> 4) & 31, kc = idx & 15;
;             *(LAS u32x4*)(WB + (gate * 32 + n) * XC_PITCH + kc * 16) = *(const u32x4*)(LruW + ((size_t)((dir * 2 + gate) * 8 + h) * 128 + q * 32 + n) * 128 + kc * 8); }
;         const float br = -LOG2E * P.lru_ba[(dir * 8 + h) * 128 + chl], bi = -LOG2E * P.lru_bx[(dir * 8 + h) * 128 + chl];
;         const float lam = P.lru_lambda[dir * 1024 + ch];
;         const float cl = -8.0f * LOG2E * log1pf(__expf(-lam));
;         float carry = 0.f;
;         LruTile cur = lru_tile(Z, ZC, b, h, dir, 0);
;         u32x4 rows[11];
;         constexpr int NIN = dir == 0 ? 2 : 4;
;         u32x4 inr[NIN];
; __device__ __forceinline__ void lru_strip(LAS unsigned char* lds, const Params& P, int strip, bool dry) {
;     const int tid = opaque_tid();
;     const int b = strip >> 5, h = (strip >> 2) & 7, q = strip & 3;
;     LAS float* CWL = (LAS float*)(lds + 256 * XC_PITCH + 2048 + 64 * XC_PITCH);
;     for (int i = tid; i < 640; i += NTHREADS) { const int k = i >> 7, c = i & 127; CWL[i] = k < 4 ? P.conv_w[k * 1024 + h * 128 + c] : P.conv_b[h * 128 + c]; }
;     LDS_BARRIER();
.LBB0_278:
	s_ashr_i32 s25, s2, 3
	v_mov_b32_e32 v128, v167
	s_bfe_u32 s26, s25, 0x30002
	s_lshl_b32 s27, s26, 7
	v_and_b32_e32 v204, 0x7f, v128
	v_or_b32_e32 v204, s27, v204
	v_lshrrev_b32_e32 v205, 7, v128
	v_lshl_or_b32 v205, v205, 10, v204
	v_lshlrev_b32_e32 v205, 2, v205
	v_lshlrev_b32_e32 v204, 2, v204
	global_load_dword v205, v205, s[52:53]
	global_load_dword v204, v204, s[54:55]
	v_readlane_b32 s0, v255, 19
	s_nop 3
	v_lshl_add_u32 v206, v128, 2, s0
	v_mov_b32_e32 v12, v167
	s_lshl_b32 s0, s25, 5
	s_and_b32 s28, s0, 0x60
	v_and_b32_e32 v15, 31, v12
	v_or_b32_e32 v17, s28, v15
	v_add_u32_e32 v14, 0x200, v12
	v_or_b32_e32 v11, s27, v17
	v_ashrrev_i32_e32 v8, 9, v12
	v_ashrrev_i32_e32 v10, 9, v14
	v_lshlrev_b32_e32 v16, 2, v11
	v_and_b32_e32 v13, 15, v12
	v_lshl_or_b32 v2, v8, 3, s26
	v_lshl_or_b32 v6, v10, 3, s26
	global_load_dword v18, v16, s[64:65]
	v_bfe_u32 v9, v12, 4, 5
	v_lshlrev_b32_e32 v64, 4, v13
	v_ashrrev_i32_e32 v3, 31, v2
	v_ashrrev_i32_e32 v7, 31, v6
	v_or_b32_e32 v4, s28, v9
	v_lshl_add_u64 v[0:1], s[38:39], 0, v[64:65]
	v_lshlrev_b64 v[2:3], 15, v[2:3]
	v_lshlrev_b64 v[6:7], 15, v[6:7]
	v_lshlrev_b32_e32 v4, 8, v4
	v_mov_b32_e32 v5, v65
	v_lshl_add_u64 v[2:3], v[0:1], 0, v[2:3]
	v_lshl_add_u64 v[0:1], v[0:1], 0, v[6:7]
	v_lshl_add_u64 v[2:3], v[2:3], 0, v[4:5]
	v_lshl_add_u64 v[4:5], v[0:1], 0, v[4:5]
	global_load_dwordx4 v[0:3], v[2:3], off
	s_nop 0
	global_load_dwordx4 v[4:7], v[4:5], off
	v_lshlrev_b32_e32 v11, 2, v12
	v_lshl_or_b32 v21, v8, 5, v9
	v_add_u32_e32 v8, s88, v64
	v_lshl_or_b32 v9, v10, 5, v9
	v_and_b32_e32 v22, 16, v11
	v_mad_u64_u32 v[10:11], s[4:5], v21, s89, v[8:9]
	v_mad_u64_u32 v[8:9], s[4:5], v9, s89, v[8:9]
	global_load_dword v9, v16, s[58:59]
	global_load_dword v11, v16, s[62:63]
	s_lshl_b32 s0, s2, 5
	s_and_b32 s0, s0, 0xe0
	s_or_b32 s1, s0, s25
	s_ashr_i32 s78, s1, 5
	s_ashr_i32 s79, s78, 31
	s_lshl_b32 s20, s26, 22
	s_lshl_b64 s[18:19], s[78:79], 19
	s_lshl_b64 s[44:45], s[78:79], 23
	v_readlane_b32 s1, v255, 18
	s_add_u32 s1, s1, s44
	s_addc_u32 s4, s33, s45
	s_lshl_b32 s5, s27, 2
	s_add_u32 s1, s1, s5
	s_addc_u32 s4, s4, 0
	s_add_u32 s5, s68, s18
	s_addc_u32 s6, s69, s19
	s_lshl_b32 s7, s27, 1
	s_add_u32 s48, s5, s7
	s_addc_u32 s49, s6, 0
	s_add_u32 s50, s48, 0x1000
	s_addc_u32 s51, s49, 0
	s_add_u32 s56, s48, 0x1800
	s_addc_u32 s57, s49, 0
	s_add_u32 s60, s48, 0x2000
	s_addc_u32 s61, s49, 0
	s_add_u32 s66, s48, 0x2800
	s_addc_u32 s67, s49, 0
	s_add_u32 s70, s48, 0x3000
	s_addc_u32 s71, s49, 0
	v_ashrrev_i32_e32 v36, 4, v12
	v_lshlrev_b32_e32 v37, 3, v13
	s_add_u32 s72, s48, 0x3800
	s_addc_u32 s73, s49, 0
	s_add_u32 s74, s48, 0x4000
	s_addc_u32 s75, s49, 0
	s_add_u32 s76, s48, 0x4800
	s_addc_u32 s77, s49, 0
	v_readfirstlane_b32 s0, v12
	s_ashr_i32 s6, s0, 6
	s_lshl_b32 s5, s28, 2
	s_add_u32 s8, s1, s5
	v_bfe_u32 v19, v12, 5, 1
	v_lshrrev_b32_e32 v20, 1, v12
	v_and_b32_e32 v33, 3, v12
	s_addc_u32 s9, s4, 0
	v_lshl_or_b32 v110, v36, 13, v37
	v_mov_b32_e32 v111, v65
	v_lshlrev_b64 v[110:111], 1, v[110:111]
	v_lshl_add_u64 v[108:109], s[48:49], 0, v[110:111]
	global_load_dwordx4 v[68:71], v[108:109], off offset:-2048
	global_load_dwordx4 v[72:75], v[108:109], off
	global_load_dwordx4 v[76:79], v[108:109], off offset:2048
	v_lshl_add_u64 v[108:109], s[50:51], 0, v[110:111]
	global_load_dwordx4 v[80:83], v[108:109], off
	v_lshl_add_u64 v[108:109], s[56:57], 0, v[110:111]
	global_load_dwordx4 v[84:87], v[108:109], off
	v_lshl_add_u64 v[108:109], s[60:61], 0, v[110:111]
	global_load_dwordx4 v[88:91], v[108:109], off
	v_lshl_add_u64 v[108:109], s[66:67], 0, v[110:111]
	global_load_dwordx4 v[92:95], v[108:109], off
	v_lshl_add_u64 v[108:109], s[70:71], 0, v[110:111]
	global_load_dwordx4 v[96:99], v[108:109], off
	v_lshl_add_u64 v[108:109], s[72:73], 0, v[110:111]
	global_load_dwordx4 v[100:103], v[108:109], off
	v_lshl_add_u64 v[108:109], s[74:75], 0, v[110:111]
	global_load_dwordx4 v[104:107], v[108:109], off
	v_lshl_add_u64 v[108:109], s[76:77], 0, v[110:111]
	global_load_dwordx4 v[108:111], v[108:109], off
	s_waitcnt vmcnt(14)
	ds_write_b128 v10, v[0:3]
	s_waitcnt vmcnt(13)
	ds_write_b128 v8, v[4:7]
	ds_write_b32 v206, v205
	v_cmp_gt_u32_e32 vcc, 0x80, v128
	s_and_saveexec_b64 s[14:15], vcc
	ds_write_b32 v206, v204 offset:2048
	s_or_b64 exec, exec, s[14:15]
	v_mul_f32_e32 v16, 0xbfb8aa3b, v18
	v_exp_f32_e32 v16, v16
	s_lshl_b32 s1, s6, 5
	s_and_b32 s0, s0, 0x3fffffc0
	v_add_u32_e32 v39, 0, v64
	v_add_f32_e32 v2, 1.0, v16
	v_add_f32_e32 v3, -1.0, v2
	v_frexp_mant_f32_e32 v4, v2
	v_cvt_f64_f32_e32 v[0:1], v2
	v_sub_f32_e32 v5, v3, v2
	v_frexp_exp_i32_f64_e32 v0, v[0:1]
	v_cmp_gt_f32_e32 vcc, s80, v4
	v_sub_f32_e32 v3, v16, v3
	v_add_f32_e32 v1, 1.0, v5
	v_subbrev_co_u32_e32 v0, vcc, 0, v0, vcc
	v_add_f32_e32 v1, v3, v1
	v_sub_u32_e32 v3, 0, v0
	v_ldexp_f32 v2, v2, v3
	v_ldexp_f32 v1, v1, v3
	v_add_f32_e32 v3, -1.0, v2
	v_add_f32_e32 v4, 1.0, v2
	v_add_f32_e32 v5, 1.0, v3
	v_add_f32_e32 v6, -1.0, v4
	v_sub_f32_e32 v5, v2, v5
	v_sub_f32_e32 v2, v2, v6
	v_add_f32_e32 v5, v1, v5
	v_add_f32_e32 v1, v1, v2
	v_add_f32_e32 v6, v4, v1
	v_rcp_f32_e32 v7, v6
	v_add_f32_e32 v2, v3, v5
	v_sub_f32_e32 v4, v6, v4
	v_sub_f32_e32 v3, v2, v3
	v_sub_f32_e32 v1, v1, v4
	v_mul_f32_e32 v4, v2, v7
	v_sub_f32_e32 v3, v5, v3
	v_mul_f32_e32 v5, v6, v4
	v_fma_f32 v8, v4, v6, -v5
	v_fmac_f32_e32 v8, v4, v1
	v_add_f32_e32 v10, v5, v8
	v_sub_f32_e32 v18, v2, v10
	v_sub_f32_e32 v2, v2, v18
	v_sub_f32_e32 v5, v10, v5
	v_sub_f32_e32 v2, v2, v10
	v_sub_f32_e32 v5, v5, v8
	v_add_f32_e32 v2, v3, v2
	v_add_f32_e32 v2, v5, v2
	v_add_f32_e32 v3, v18, v2
	v_mul_f32_e32 v5, v7, v3
	v_mul_f32_e32 v10, v6, v5
	v_fma_f32 v6, v5, v6, -v10
; template <int dir>
; __device__ __forceinline__ void lru_pass(LAS unsigned char* lds, const Params& P, int b, int h, int q, bool dry) {
;     ...
;         const float br = -LOG2E * P.lru_ba[(dir * 8 + h) * 128 + chl], bi = -LOG2E * P.lru_bx[(dir * 8 + h) * 128 + chl];
;         const float lam = P.lru_lambda[dir * 1024 + ch];
;         const float cl = -8.0f * LOG2E * log1pf(__expf(-lam));
;         float carry = 0.f;
;         LruTile cur = lru_tile(Z, ZC, b, h, dir, 0);
;         u32x4 rows[11];
;         constexpr int NIN = dir == 0 ? 2 : 4;
;         u32x4 inr[NIN];
;         lru_load_rows(rows, cur, tr, cgp);
; #pragma unroll
;         for (int i = 0; i < NIN; ++i) inr[i] = (u32x4){0u, 0u, 0u, 0u};
	v_fmac_f32_e32 v6, v5, v1
	v_add_f32_e32 v1, v10, v6
	v_sub_f32_e32 v8, v18, v3
	v_sub_f32_e32 v18, v3, v1
	v_sub_f32_e32 v3, v3, v18
	v_add_f32_e32 v2, v2, v8
	v_sub_f32_e32 v10, v1, v10
	v_sub_f32_e32 v1, v3, v1
	v_sub_f32_e32 v6, v10, v6
	v_add_f32_e32 v1, v2, v1
	v_cvt_f32_i32_e32 v0, v0
	v_add_f32_e32 v8, v4, v5
	v_add_f32_e32 v1, v6, v1
	v_add_f32_e32 v1, v18, v1
	v_sub_f32_e32 v2, v8, v4
	v_mul_f32_e32 v1, v7, v1
	v_sub_f32_e32 v2, v5, v2
	v_add_f32_e32 v1, v2, v1
	v_mul_f32_e32 v5, 0x3f317218, v0
	v_add_f32_e32 v2, v8, v1
	v_fma_f32 v6, v0, s81, -v5
	v_fmac_f32_e32 v6, 0xb102e308, v0
	v_sub_f32_e32 v0, v2, v8
	v_mul_f32_e32 v3, v2, v2
	v_sub_f32_e32 v0, v1, v0
	v_add_f32_e32 v1, v5, v6
	v_fmamk_f32 v4, v3, 0x3e9b6dac, v200
	v_sub_f32_e32 v5, v1, v5
	v_fmaak_f32 v4, v3, v4, 0x3f2aaada
	v_sub_f32_e32 v5, v6, v5
	v_ldexp_f32 v6, v2, 1
	v_mul_f32_e32 v2, v2, v3
	v_mul_f32_e32 v2, v2, v4
	v_add_f32_e32 v3, v6, v2
	v_sub_f32_e32 v4, v3, v6
	v_ldexp_f32 v0, v0, 1
	v_sub_f32_e32 v2, v2, v4
	v_add_f32_e32 v0, v0, v2
	v_add_f32_e32 v2, v3, v0
	v_sub_f32_e32 v3, v2, v3
	v_sub_f32_e32 v0, v0, v3
	v_add_f32_e32 v3, v1, v2
	v_sub_f32_e32 v4, v3, v1
	v_sub_f32_e32 v6, v3, v4
	v_sub_f32_e32 v1, v1, v6
	v_sub_f32_e32 v2, v2, v4
	v_add_f32_e32 v1, v2, v1
	v_add_f32_e32 v2, v5, v0
	v_sub_f32_e32 v4, v2, v5
	v_add_f32_e32 v1, v2, v1
	v_sub_f32_e32 v6, v2, v4
	v_add_f32_e32 v2, v3, v1
	v_sub_f32_e32 v5, v5, v6
	v_sub_f32_e32 v0, v0, v4
	v_sub_f32_e32 v3, v2, v3
	v_add_f32_e32 v0, v0, v5
	v_sub_f32_e32 v1, v1, v3
	v_add_f32_e32 v0, v0, v1
	v_add_f32_e32 v0, v2, v0
	v_cmp_neq_f32_e32 vcc, s91, v16
	v_mov_b32_e32 v1, v65
	v_lshlrev_b32_e32 v41, 4, v19
	v_cndmask_b32_e32 v0, v201, v0, vcc
	v_cmp_ngt_f32_e32 vcc, -1.0, v16
	s_cmp_eq_u32 s6, 7
	v_or_b32_e32 v35, s1, v41
	v_cndmask_b32_e32 v0, v202, v0, vcc
	v_cmp_neq_f32_e32 vcc, -1.0, v16
	v_ashrrev_i32_e32 v32, 2, v12
	v_ashrrev_i32_e32 v34, 2, v14
	v_cndmask_b32_e32 v0, v203, v0, vcc
	v_cmp_lt_f32_e64 vcc, |v16|, s92
	v_lshlrev_b32_e32 v53, 4, v33
	v_mul_lo_u32 v48, v32, s87
	v_cndmask_b32_e32 v6, v0, v16, vcc
	v_lshlrev_b32_e32 v1, 2, v15
	v_lshlrev_b32_e32 v2, 4, v12
	v_add_u32_e32 v140, s94, v1
	v_and_b32_e32 v3, 48, v2
	v_and_b32_e32 v64, 0x70, v2
	v_and_or_b32 v2, v20, 12, v33
	v_or3_b32 v2, v2, v22, s1
	v_lshl_add_u32 v147, s0, 2, v140
	s_cselect_b64 s[0:1], -1, 0
	s_cmp_eq_u32 s6, 6
	s_cselect_b64 s[16:17], -1, 0
	s_cmp_eq_u32 s6, 5
	s_cselect_b64 s[4:5], -1, 0
	s_cmp_eq_u32 s6, 4
	v_lshl_add_u64 v[130:131], s[8:9], 0, v[64:65]
	s_cselect_b64 s[8:9], -1, 0
	s_cmp_eq_u32 s6, 3
	s_cselect_b64 s[10:11], -1, 0
	s_cmp_eq_u32 s6, 2
	s_cselect_b64 s[12:13], -1, 0
	s_cmp_eq_u32 s6, 1
	s_cselect_b64 s[14:15], -1, 0
	s_add_u32 s46, s20, s18
	s_addc_u32 s47, 0, s19
	s_lshl_b32 s6, s2, 3
	v_ashrrev_i32_e32 v33, 31, v32
	v_mul_lo_u32 v50, v35, s89
	v_mul_lo_u32 v51, v35, s87
	v_mul_lo_u32 v52, v35, s30
	v_ashrrev_i32_e32 v35, 31, v34
	s_bfe_u32 s29, s2, 0x20003
	s_and_b32 s6, s6, 0xc0
	v_lshlrev_b64 v[32:33], 8, v[32:33]
	v_mul_lo_u32 v2, v2, s89
	v_add_u32_e32 v46, s96, v1
	v_mul_lo_u32 v49, v34, s87
	v_add_u32_e32 v1, 0x400, v12
	v_lshlrev_b64 v[34:35], 8, v[34:35]
	v_lshl_add_u64 v[32:33], s[46:47], 0, v[32:33]
	s_add_u32 s18, s82, s46
	v_lshlrev_b32_e32 v38, 5, v13
	v_add_u32_e32 v129, s96, v64
	v_add_u32_e32 v42, 0, v2
	v_mov_b32_e32 v2, s88
	v_ashrrev_i32_e32 v143, 3, v1
	v_add_u32_e32 v1, 0x600, v12
	v_lshl_add_u64 v[34:35], s[46:47], 0, v[34:35]
	v_or3_b32 v32, v32, s6, v53
	v_lshl_or_b32 v64, v36, 10, v37
	s_addc_u32 s19, s83, s47
	v_mov_b32_e32 v66, v65
	v_mov_b32_e32 v67, v65
	s_waitcnt vmcnt(12)
	v_mul_f32_e32 v0, 0xbfb8aa3b, v9
	s_waitcnt vmcnt(11)
	v_mul_f32_e32 v16, 0xbfb8aa3b, v11
	v_add_u32_e32 v40, s95, v3
	v_mad_u32_u24 v43, v15, s89, v2
	v_lshl_add_u32 v44, v17, 1, 0
	v_lshl_add_u32 v45, v15, 1, s95
	v_mul_lo_u32 v47, v36, s93
	v_ashrrev_i32_e32 v148, 3, v12
	v_ashrrev_i32_e32 v145, 3, v14
	v_ashrrev_i32_e32 v141, 3, v1
	v_or3_b32 v34, v34, s6, v53
	v_lshl_add_u64 v[134:135], s[40:41], 0, v[32:33]
	v_lshl_add_u64 v[136:137], v[64:65], 1, s[18:19]
	v_mov_b32_e32 v64, v65
	v_add_u32_e32 v32, 0, v38
	v_mov_b64_e32 v[114:115], v[66:67]
	v_mov_b64_e32 v[118:119], v[66:67]
	s_mov_b32 s90, 0
	v_mul_f32_e32 v138, 0xc138aa3b, v6
	v_lshl_add_u32 v139, v36, 3, -1
	v_cmp_eq_u32_e32 vcc, 0, v19
	v_mul_lo_u32 v149, v148, s30
	v_mul_lo_u32 v146, v145, s30
	v_mul_lo_u32 v144, v143, s30
	v_mul_lo_u32 v142, v141, s30
	v_mov_b32_e32 v1, v0
	v_mov_b32_e32 v2, v0
	v_mov_b32_e32 v3, v0
	v_mov_b32_e32 v4, v0
	v_mov_b32_e32 v5, v0
	v_mov_b32_e32 v6, v0
	v_mov_b32_e32 v7, v0
	v_mov_b32_e32 v8, v0
	v_mov_b32_e32 v9, v0
	v_mov_b32_e32 v10, v0
	v_mov_b32_e32 v11, v0
	v_mov_b32_e32 v12, v0
	v_mov_b32_e32 v13, v0
	v_mov_b32_e32 v14, v0
	v_mov_b32_e32 v15, v0
	v_mov_b32_e32 v17, v16
	v_mov_b32_e32 v18, v16
	v_mov_b32_e32 v19, v16
	v_mov_b32_e32 v20, v16
	v_mov_b32_e32 v21, v16
	v_mov_b32_e32 v22, v16
	v_mov_b32_e32 v23, v16
	v_mov_b32_e32 v24, v16
	v_mov_b32_e32 v25, v16
	v_mov_b32_e32 v26, v16
	v_mov_b32_e32 v27, v16
	v_mov_b32_e32 v28, v16
	v_mov_b32_e32 v29, v16
	v_mov_b32_e32 v30, v16
	v_mov_b32_e32 v31, v16
	v_lshl_add_u64 v[132:133], s[40:41], 0, v[34:35]
	s_movk_i32 s92, 0x100
	v_mov_b32_e32 v165, 0
	s_mov_b64 s[80:81], 0
	v_add_u32_e32 v150, 0x15c00, v32
	v_add_u32_e32 v151, v39, v47
	v_add_u32_e32 v158, v40, v48
	v_add_u32_e32 v159, v40, v49
	v_add_u32_e32 v160, v42, v41
	v_add_u32_e32 v161, v43, v41
	v_add_u32_e32 v162, v44, v50
	v_add_u32_e32 v163, v45, v51
	v_add_u32_e32 v164, v46, v52
	v_mov_b64_e32 v[112:113], v[64:65]
	v_mov_b64_e32 v[116:117], v[64:65]
	s_mov_b32 s91, 0
	s_mov_b32 s93, 0
	s_mov_b32 s97, 0
; #define LAS __attribute__((address_space(3)))
; __device__ __forceinline__ unsigned cvt_pk_bf16(float lo, float hi) { unsigned r; asm volatile("v_cvt_pk_bf16_f32 %0, %1, %2" : "=v"(r) : "v"(lo), "v"(hi)); return r; }
; __device__ __forceinline__ float bf_lo(unsigned u) { return __uint_as_float(u << 16); }
; __device__ __forceinline__ float bf_hi(unsigned u) { return __uint_as_float(u & 0xffff0000u); }
; template <int dir>
; __device__ __forceinline__ void lru_pass(LAS unsigned char* lds, const Params& P, int b, int h, int q, bool dry) {
;     ...
;         for (int sc = 0; sc < 9; ++sc) {
;             const bool isctx = (sc == 0);
;             const int t0 = cur.t0;
; #pragma unroll
;             for (int j = 0; j < 11; ++j) { if (j != 0 && j < 9) continue;
;                 const int t = t0 + tr * 8 - 1 + j; if (t < 0 || t >= cur.L) rows[j] = (u32x4){0u, 0u, 0u, 0u}; }
;             f32x2 cw2[4][4], cb2[4];
; #pragma unroll
;             for (int k = 0; k < 5; ++k) { const f32x4 a = *(const LAS f32x4*)(CWL + k * 128 + cgp * 8), c2 = *(const LAS f32x4*)(CWL + k * 128 + cgp * 8 + 4);
;                 if (k < 4) { cw2[k][0] = (f32x2){a[0], a[1]}; cw2[k][1] = (f32x2){a[2], a[3]}; cw2[k][2] = (f32x2){c2[0], c2[1]}; cw2[k][3] = (f32x2){c2[2], c2[3]}; }
;                 else { cb2[0] = (f32x2){a[0], a[1]}; cb2[1] = (f32x2){a[2], a[3]}; cb2[2] = (f32x2){c2[0], c2[1]}; cb2[3] = (f32x2){c2[2], c2[3]}; } }
; #pragma unroll
;             for (int j = 0; j < 8; ++j) {
;                 f32x2 o0 = cb2[0], o1 = cb2[1], o2 = cb2[2], o3 = cb2[3];
; #pragma unroll
;                 for (int k = 0; k < 4; ++k) { const u32x4 rr = rows[j + k];
;                     o0 = cw2[k][0] * (f32x2){bf_lo(rr.x), bf_hi(rr.x)} + o0; o1 = cw2[k][1] * (f32x2){bf_lo(rr.y), bf_hi(rr.y)} + o1;
;                     o2 = cw2[k][2] * (f32x2){bf_lo(rr.z), bf_hi(rr.z)} + o2; o3 = cw2[k][3] * (f32x2){bf_lo(rr.w), bf_hi(rr.w)} + o3; }
;     ...
;                 for (int v = 0; v < 16; ++v) { const float hv = fmaf(zi[v], cin, zr[v]);
;                     const int s = sbase + v; const int tl = dir == 0 ? s : 255 - s;
;                     if (dir == 0) *(LAS unsigned*)(TOUT + tl * IO_WP + nl * 4) = (cvt_pk_bf16(hv, 0.f) & 0xffffu) | (pk[v] << 16);
;                     else *(LAS bf16_t*)(TOUT + tl * IO_NP + nl * 2) = f2bf((bf_lo(pk[v]) + hv) * bf_hi(pk[v])); }
	v_lshrrev_b32_e32 v254, 8, v167
	v_mul_u32_u24_e32 v252, 0x1400, v254
	v_add_u32_e32 v158, v158, v252
	v_add_u32_e32 v159, v159, v252
	v_add_u32_e32 v159, 0xffffec00, v159
	v_lshlrev_b32_e32 v252, 14, v254
	v_mov_b32_e32 v253, 0
	v_lshl_add_u64 v[134:135], v[252:253], 0, v[134:135]
	v_lshl_add_u64 v[132:133], v[252:253], 0, v[132:133]
	s_mov_b32 s18, 0xffffc000
	s_mov_b32 s19, -1
	v_lshl_add_u64 v[132:133], v[132:133], 0, s[18:19]
	v_mul_u32_u24_e32 v252, 0x3600, v254
	v_add_u32_e32 v149, v149, v252
	v_add_u32_e32 v146, v146, v252
	v_add_u32_e32 v144, v144, v252
	v_add_u32_e32 v142, v142, v252
	v_add_u32_e32 v146, 0xffffee00, v146
	v_add_u32_e32 v144, 0xffffdc00, v144
	v_add_u32_e32 v142, 0xffffca00, v142
	v_mul_u32_u24_e32 v252, 0x60, v254
	v_add_u32_e32 v148, v148, v252
	v_add_u32_e32 v145, v145, v252
	v_add_u32_e32 v143, v143, v252
	v_add_u32_e32 v141, v141, v252
	v_add_u32_e32 v145, 0xffffffe0, v145
	v_add_u32_e32 v143, 0xffffffc0, v143
	v_add_u32_e32 v141, 0xffffffa0, v141
	v_lshrrev_b32_e32 v253, 6, v167
	s_nop 1
	v_readfirstlane_b32 s18, v253
	s_lshr_b32 s101, s18, 2
	s_or_b32 s19, s18, 4
	s_cmp_eq_u32 s19, 7
	s_cselect_b64 s[0:1], -1, 0
	s_cmp_eq_u32 s19, 6
	s_cselect_b64 s[16:17], -1, 0
	s_cmp_eq_u32 s19, 5
	s_cselect_b64 s[4:5], -1, 0
	s_cmp_eq_u32 s19, 4
	s_cselect_b64 s[8:9], -1, 0
	s_mov_b64 s[10:11], 0
	s_mov_b64 s[12:13], 0
	s_mov_b64 s[14:15], 0
	v_and_b32_e32 v252, 31, v167
	v_lshlrev_b32_e32 v253, 2, v252
	v_sub_u32_e32 v164, v164, v253
	v_subrev_u32_e32 v164, s96, v164
	v_mul_u32_u24_e32 v164, 0x1c8, v164
	v_lshrrev_b32_e32 v164, 16, v164
	v_mul_u32_u24_e32 v164, 0x50, v164
	v_lshl_add_u32 v164, v252, 1, v164
	v_add_u32_e32 v164, s95, v164
	s_mov_b32 s98, 0
	s_cmp_eq_u32 s101, 0
	s_cselect_b32 s99, 0x14400, 0
	s_cselect_b32 s100, 0, 0x400
	v_add_u32_e32 v253, 0x14000, v147
	v_mov_b32_e32 v254, 1.0
	v_mov_b32_e32 v252, 0
	ds_write2_b32 v253, v254, v252 offset1:32
	s_waitcnt lgkmcnt(0)
	s_barrier
	s_cmp_eq_u32 s101, 0
	s_cbranch_scc1 .Lpp_f_nox
	s_barrier
.Lpp_f_nox:
.LBB0_292:
	v_add_u32_e32 v32, s97, v139
	v_cmp_lt_i32_e64 s[18:19], -1, v32
	v_cmp_gt_i32_e64 s[20:21], s92, v32
	s_and_b64 s[18:19], s[18:19], s[20:21]
	v_add_u32_e32 v33, 9, v32
	s_waitcnt vmcnt(10)
	v_cndmask_b32_e64 v71, 0, v71, s[18:19]
	v_cndmask_b32_e64 v70, 0, v70, s[18:19]
	v_cndmask_b32_e64 v69, 0, v69, s[18:19]
	v_cndmask_b32_e64 v68, 0, v68, s[18:19]
	v_cmp_lt_i32_e64 s[18:19], -10, v32
	v_cmp_gt_i32_e64 s[20:21], s92, v33
	s_and_b64 s[18:19], s[18:19], s[20:21]
	v_add_u32_e32 v33, 10, v32
	s_waitcnt vmcnt(1)
	v_cndmask_b32_e64 v107, 0, v107, s[18:19]
	v_cndmask_b32_e64 v106, 0, v106, s[18:19]
	v_cndmask_b32_e64 v105, 0, v105, s[18:19]
	v_cndmask_b32_e64 v104, 0, v104, s[18:19]
	v_cmp_lt_i32_e64 s[18:19], -11, v32
	v_cmp_gt_i32_e64 s[20:21], s92, v33
	ds_read_b128 v[60:63], v150
	ds_read_b128 v[52:55], v150 offset:16
	ds_read_b128 v[44:47], v150 offset:528
	ds_read_b128 v[56:59], v150 offset:512
	ds_read_b128 v[40:43], v150 offset:1040
	ds_read_b128 v[48:51], v150 offset:1024
	ds_read_b128 v[120:123], v150 offset:2064
	ds_read_b128 v[124:127], v150 offset:2048
	ds_read_b128 v[32:35], v150 offset:1552
	ds_read_b128 v[36:39], v150 offset:1536
	v_lshlrev_b32_e32 v66, 16, v68
	v_and_b32_e32 v67, 0xffff0000, v68
	v_lshlrev_b32_e32 v154, 16, v69
	v_and_b32_e32 v155, 0xffff0000, v69
	v_lshlrev_b32_e32 v168, 16, v70
	v_and_b32_e32 v169, 0xffff0000, v70
	s_waitcnt lgkmcnt(2)
	v_pk_fma_f32 v[66:67], v[60:61], v[66:67], v[124:125]
	v_pk_fma_f32 v[154:155], v[62:63], v[154:155], v[126:127]
	v_pk_fma_f32 v[168:169], v[52:53], v[168:169], v[120:121]
	v_lshlrev_b32_e32 v170, 16, v71
	v_and_b32_e32 v171, 0xffff0000, v71
	v_lshlrev_b32_e32 v172, 16, v72
	v_and_b32_e32 v173, 0xffff0000, v72
	v_lshlrev_b32_e32 v174, 16, v73
	v_and_b32_e32 v175, 0xffff0000, v73
	v_lshlrev_b32_e32 v176, 16, v74
	v_and_b32_e32 v177, 0xffff0000, v74
	v_pk_fma_f32 v[170:171], v[54:55], v[170:171], v[122:123]
	v_pk_fma_f32 v[66:67], v[56:57], v[172:173], v[66:67]
	v_pk_fma_f32 v[154:155], v[58:59], v[174:175], v[154:155]
	v_pk_fma_f32 v[168:169], v[44:45], v[176:177], v[168:169]
	v_lshlrev_b32_e32 v178, 16, v75
	v_and_b32_e32 v179, 0xffff0000, v75
	v_lshlrev_b32_e32 v180, 16, v76
	v_and_b32_e32 v181, 0xffff0000, v76
	v_lshlrev_b32_e32 v182, 16, v77
	v_and_b32_e32 v183, 0xffff0000, v77
	v_lshlrev_b32_e32 v184, 16, v78
	v_and_b32_e32 v185, 0xffff0000, v78
	v_pk_fma_f32 v[170:171], v[46:47], v[178:179], v[170:171]
	v_pk_fma_f32 v[66:67], v[48:49], v[180:181], v[66:67]
	v_pk_fma_f32 v[154:155], v[50:51], v[182:183], v[154:155]
	v_pk_fma_f32 v[168:169], v[40:41], v[184:185], v[168:169]
	v_lshlrev_b32_e32 v186, 16, v79
	v_and_b32_e32 v187, 0xffff0000, v79
	v_lshlrev_b32_e32 v188, 16, v80
	v_and_b32_e32 v189, 0xffff0000, v80
	v_lshlrev_b32_e32 v190, 16, v81
	v_and_b32_e32 v191, 0xffff0000, v81
	v_lshlrev_b32_e32 v192, 16, v82
	v_and_b32_e32 v193, 0xffff0000, v82
	v_pk_fma_f32 v[170:171], v[42:43], v[186:187], v[170:171]
	s_waitcnt lgkmcnt(0)
; #define LAS __attribute__((address_space(3)))
; __device__ __forceinline__ unsigned cvt_pk_bf16(float lo, float hi) { unsigned r; asm volatile("v_cvt_pk_bf16_f32 %0, %1, %2" : "=v"(r) : "v"(lo), "v"(hi)); return r; }
; __device__ __forceinline__ float bf_lo(unsigned u) { return __uint_as_float(u << 16); }
; __device__ __forceinline__ float bf_hi(unsigned u) { return __uint_as_float(u & 0xffff0000u); }
; template <int dir>
; __device__ __forceinline__ void lru_pass(LAS unsigned char* lds, const Params& P, int b, int h, int q, bool dry) {
;     ...
;             for (int j = 0; j < 8; ++j) {
;                 f32x2 o0 = cb2[0], o1 = cb2[1], o2 = cb2[2], o3 = cb2[3];
; #pragma unroll
;                 for (int k = 0; k < 4; ++k) { const u32x4 rr = rows[j + k];
;                     o0 = cw2[k][0] * (f32x2){bf_lo(rr.x), bf_hi(rr.x)} + o0; o1 = cw2[k][1] * (f32x2){bf_lo(rr.y), bf_hi(rr.y)} + o1;
;                     o2 = cw2[k][2] * (f32x2){bf_lo(rr.z), bf_hi(rr.z)} + o2; o3 = cw2[k][3] * (f32x2){bf_lo(rr.w), bf_hi(rr.w)} + o3; }
;                 u32x4 w; w.x = cvt_pk_bf16(o0[0], o0[1]); w.y = cvt_pk_bf16(o1[0], o1[1]); w.z = cvt_pk_bf16(o2[0], o2[1]); w.w = cvt_pk_bf16(o3[0], o3[1]);
;                 *(LAS u32x4*)(XC + (tr * 8 + j) * XC_PITCH + cgp * 16) = w;
;             }
	v_pk_fma_f32 v[66:67], v[36:37], v[188:189], v[66:67]
	v_pk_fma_f32 v[154:155], v[38:39], v[190:191], v[154:155]
	v_pk_fma_f32 v[194:195], v[32:33], v[192:193], v[168:169]
	v_lshlrev_b32_e32 v196, 16, v83
	v_and_b32_e32 v197, 0xffff0000, v83
	v_cvt_pk_bf16_f32 v168, v66, v67
	v_cvt_pk_bf16_f32 v169, v154, v155
	v_pk_fma_f32 v[198:199], v[34:35], v[196:197], v[170:171]
	v_cvt_pk_bf16_f32 v170, v194, v195
	v_pk_fma_f32 v[66:67], v[60:61], v[172:173], v[124:125]
	v_cvt_pk_bf16_f32 v171, v198, v199
	ds_write_b128 v151, v[168:171]
	v_pk_fma_f32 v[154:155], v[62:63], v[174:175], v[126:127]
	v_pk_fma_f32 v[168:169], v[52:53], v[176:177], v[120:121]
	v_pk_fma_f32 v[170:171], v[54:55], v[178:179], v[122:123]
	v_pk_fma_f32 v[66:67], v[56:57], v[180:181], v[66:67]
	v_pk_fma_f32 v[154:155], v[58:59], v[182:183], v[154:155]
	v_pk_fma_f32 v[168:169], v[44:45], v[184:185], v[168:169]
	v_pk_fma_f32 v[170:171], v[46:47], v[186:187], v[170:171]
	v_pk_fma_f32 v[66:67], v[48:49], v[188:189], v[66:67]
	v_pk_fma_f32 v[154:155], v[50:51], v[190:191], v[154:155]
	v_pk_fma_f32 v[168:169], v[40:41], v[192:193], v[168:169]
	v_lshlrev_b32_e32 v172, 16, v84
	v_and_b32_e32 v173, 0xffff0000, v84
	v_lshlrev_b32_e32 v174, 16, v85
	v_and_b32_e32 v175, 0xffff0000, v85
	v_lshlrev_b32_e32 v176, 16, v86
	v_and_b32_e32 v177, 0xffff0000, v86
	v_pk_fma_f32 v[170:171], v[42:43], v[196:197], v[170:171]
	v_pk_fma_f32 v[66:67], v[36:37], v[172:173], v[66:67]
	v_pk_fma_f32 v[154:155], v[38:39], v[174:175], v[154:155]
	v_pk_fma_f32 v[178:179], v[32:33], v[176:177], v[168:169]
	v_lshlrev_b32_e32 v194, 16, v87
	v_and_b32_e32 v195, 0xffff0000, v87
	v_cvt_pk_bf16_f32 v168, v66, v67
	v_cvt_pk_bf16_f32 v169, v154, v155
	v_pk_fma_f32 v[198:199], v[34:35], v[194:195], v[170:171]
	v_cvt_pk_bf16_f32 v170, v178, v179
	v_pk_fma_f32 v[66:67], v[60:61], v[180:181], v[124:125]
	v_cvt_pk_bf16_f32 v171, v198, v199
	ds_write_b128 v151, v[168:171] offset:272
	v_pk_fma_f32 v[154:155], v[62:63], v[182:183], v[126:127]
	v_pk_fma_f32 v[168:169], v[52:53], v[184:185], v[120:121]
	v_pk_fma_f32 v[170:171], v[54:55], v[186:187], v[122:123]
	v_pk_fma_f32 v[66:67], v[56:57], v[188:189], v[66:67]
	v_pk_fma_f32 v[154:155], v[58:59], v[190:191], v[154:155]
	v_pk_fma_f32 v[168:169], v[44:45], v[192:193], v[168:169]
	v_pk_fma_f32 v[170:171], v[46:47], v[196:197], v[170:171]
	v_pk_fma_f32 v[66:67], v[48:49], v[172:173], v[66:67]
	v_pk_fma_f32 v[154:155], v[50:51], v[174:175], v[154:155]
	v_pk_fma_f32 v[168:169], v[40:41], v[176:177], v[168:169]
	v_lshlrev_b32_e32 v178, 16, v88
	v_and_b32_e32 v179, 0xffff0000, v88
	v_lshlrev_b32_e32 v180, 16, v89
	v_and_b32_e32 v181, 0xffff0000, v89
	v_lshlrev_b32_e32 v182, 16, v90
	v_and_b32_e32 v183, 0xffff0000, v90
	v_pk_fma_f32 v[170:171], v[42:43], v[194:195], v[170:171]
	v_pk_fma_f32 v[66:67], v[36:37], v[178:179], v[66:67]
	v_pk_fma_f32 v[154:155], v[38:39], v[180:181], v[154:155]
	v_pk_fma_f32 v[184:185], v[32:33], v[182:183], v[168:169]
	v_lshlrev_b32_e32 v186, 16, v91
	v_and_b32_e32 v187, 0xffff0000, v91
	v_cvt_pk_bf16_f32 v168, v66, v67
	v_cvt_pk_bf16_f32 v169, v154, v155
	v_pk_fma_f32 v[198:199], v[34:35], v[186:187], v[170:171]
	v_cvt_pk_bf16_f32 v170, v184, v185
	v_pk_fma_f32 v[66:67], v[60:61], v[188:189], v[124:125]
	v_cvt_pk_bf16_f32 v171, v198, v199
	ds_write_b128 v151, v[168:171] offset:544
	v_pk_fma_f32 v[154:155], v[62:63], v[190:191], v[126:127]
	v_pk_fma_f32 v[168:169], v[52:53], v[192:193], v[120:121]
	v_pk_fma_f32 v[170:171], v[54:55], v[196:197], v[122:123]
	v_pk_fma_f32 v[66:67], v[56:57], v[172:173], v[66:67]
	v_pk_fma_f32 v[154:155], v[58:59], v[174:175], v[154:155]
	v_pk_fma_f32 v[168:169], v[44:45], v[176:177], v[168:169]
	v_pk_fma_f32 v[170:171], v[46:47], v[194:195], v[170:171]
	v_pk_fma_f32 v[66:67], v[48:49], v[178:179], v[66:67]
	v_pk_fma_f32 v[154:155], v[50:51], v[180:181], v[154:155]
	v_pk_fma_f32 v[168:169], v[40:41], v[182:183], v[168:169]
	v_lshlrev_b32_e32 v184, 16, v92
	v_and_b32_e32 v185, 0xffff0000, v92
	v_lshlrev_b32_e32 v188, 16, v93
	v_and_b32_e32 v189, 0xffff0000, v93
	v_lshlrev_b32_e32 v190, 16, v94
	v_and_b32_e32 v191, 0xffff0000, v94
	v_pk_fma_f32 v[170:171], v[42:43], v[186:187], v[170:171]
	v_pk_fma_f32 v[66:67], v[36:37], v[184:185], v[66:67]
	v_pk_fma_f32 v[154:155], v[38:39], v[188:189], v[154:155]
	v_pk_fma_f32 v[192:193], v[32:33], v[190:191], v[168:169]
	v_lshlrev_b32_e32 v196, 16, v95
	v_and_b32_e32 v197, 0xffff0000, v95
	v_cvt_pk_bf16_f32 v168, v66, v67
	v_cvt_pk_bf16_f32 v169, v154, v155
	v_pk_fma_f32 v[198:199], v[34:35], v[196:197], v[170:171]
	v_cvt_pk_bf16_f32 v170, v192, v193
	v_pk_fma_f32 v[66:67], v[60:61], v[172:173], v[124:125]
	v_cvt_pk_bf16_f32 v171, v198, v199
	ds_write_b128 v151, v[168:171] offset:816
	v_pk_fma_f32 v[154:155], v[62:63], v[174:175], v[126:127]
	v_pk_fma_f32 v[168:169], v[52:53], v[176:177], v[120:121]
	v_pk_fma_f32 v[170:171], v[54:55], v[194:195], v[122:123]
	v_pk_fma_f32 v[66:67], v[56:57], v[178:179], v[66:67]
	v_pk_fma_f32 v[154:155], v[58:59], v[180:181], v[154:155]
	v_pk_fma_f32 v[168:169], v[44:45], v[182:183], v[168:169]
	v_pk_fma_f32 v[170:171], v[46:47], v[186:187], v[170:171]
	v_pk_fma_f32 v[66:67], v[48:49], v[184:185], v[66:67]
	v_pk_fma_f32 v[154:155], v[50:51], v[188:189], v[154:155]
	v_pk_fma_f32 v[168:169], v[40:41], v[190:191], v[168:169]
	v_lshlrev_b32_e32 v172, 16, v96
	v_and_b32_e32 v173, 0xffff0000, v96
	v_lshlrev_b32_e32 v174, 16, v97
	v_and_b32_e32 v175, 0xffff0000, v97
	v_lshlrev_b32_e32 v176, 16, v98
	v_and_b32_e32 v177, 0xffff0000, v98
	v_pk_fma_f32 v[170:171], v[42:43], v[196:197], v[170:171]
	v_pk_fma_f32 v[66:67], v[36:37], v[172:173], v[66:67]
; #define LAS __attribute__((address_space(3)))
; __device__ __forceinline__ unsigned cvt_pk_bf16(float lo, float hi) { unsigned r; asm volatile("v_cvt_pk_bf16_f32 %0, %1, %2" : "=v"(r) : "v"(lo), "v"(hi)); return r; }
; __device__ __forceinline__ float bf_lo(unsigned u) { return __uint_as_float(u << 16); }
; __device__ __forceinline__ float bf_hi(unsigned u) { return __uint_as_float(u & 0xffff0000u); }
; template <int dir>
; __device__ __forceinline__ void lru_pass(LAS unsigned char* lds, const Params& P, int b, int h, int q, bool dry) {
;     ...
;                 for (int k = 0; k < 4; ++k) { const u32x4 rr = rows[j + k];
;                     o0 = cw2[k][0] * (f32x2){bf_lo(rr.x), bf_hi(rr.x)} + o0; o1 = cw2[k][1] * (f32x2){bf_lo(rr.y), bf_hi(rr.y)} + o1;
;                     o2 = cw2[k][2] * (f32x2){bf_lo(rr.z), bf_hi(rr.z)} + o2; o3 = cw2[k][3] * (f32x2){bf_lo(rr.w), bf_hi(rr.w)} + o3; }
;                 u32x4 w; w.x = cvt_pk_bf16(o0[0], o0[1]); w.y = cvt_pk_bf16(o1[0], o1[1]); w.z = cvt_pk_bf16(o2[0], o2[1]); w.w = cvt_pk_bf16(o3[0], o3[1]);
;                 *(LAS u32x4*)(XC + (tr * 8 + j) * XC_PITCH + cgp * 16) = w;
;             }
; #pragma unroll
;             for (int i = 0; i < NIN; ++i) { const int id = tid + i * NTHREADS;
;                 if (dir == 0) *(LAS u32x4*)(TIN + (id >> 2) * IO_NP + (id & 3) * 16) = inr[i];
;                 else *(LAS u32x4*)(TIN + (id >> 3) * IO_WP + (id & 7) * 16) = inr[i]; }
;             LruTile nxt = cur;
;             if (sc < 8) { nxt = lru_tile(Z, ZC, b, h, dir, sc + 1); lru_load_rows(rows, nxt, tr, cgp);
; #pragma unroll
;                 for (int i = 0; i < NIN; ++i) { const int id = tid + i * NTHREADS;
;                     if (dir == 0) inr[i] = *(const u32x4*)(Zg + (size_t)(nxt.t0 + (id >> 2)) * 128 + (id & 3) * 8);
;                     else inr[i] = *(const u32x4*)(Hg + (size_t)(nxt.t0 + (id >> 3)) * DM + (id & 7) * 4); } }
	v_pk_fma_f32 v[154:155], v[38:39], v[174:175], v[154:155]
	v_pk_fma_f32 v[192:193], v[32:33], v[176:177], v[168:169]
	v_lshlrev_b32_e32 v194, 16, v99
	v_and_b32_e32 v195, 0xffff0000, v99
	v_cvt_pk_bf16_f32 v168, v66, v67
	v_cvt_pk_bf16_f32 v169, v154, v155
	v_pk_fma_f32 v[198:199], v[34:35], v[194:195], v[170:171]
	v_cvt_pk_bf16_f32 v170, v192, v193
	v_pk_fma_f32 v[66:67], v[60:61], v[178:179], v[124:125]
	v_cvt_pk_bf16_f32 v171, v198, v199
	ds_write_b128 v151, v[168:171] offset:1088
	v_pk_fma_f32 v[154:155], v[62:63], v[180:181], v[126:127]
	v_pk_fma_f32 v[168:169], v[52:53], v[182:183], v[120:121]
	v_pk_fma_f32 v[170:171], v[54:55], v[186:187], v[122:123]
	v_pk_fma_f32 v[66:67], v[56:57], v[184:185], v[66:67]
	v_pk_fma_f32 v[154:155], v[58:59], v[188:189], v[154:155]
	v_pk_fma_f32 v[168:169], v[44:45], v[190:191], v[168:169]
	v_pk_fma_f32 v[170:171], v[46:47], v[196:197], v[170:171]
	v_pk_fma_f32 v[66:67], v[48:49], v[172:173], v[66:67]
	v_pk_fma_f32 v[154:155], v[50:51], v[174:175], v[154:155]
	v_pk_fma_f32 v[168:169], v[40:41], v[176:177], v[168:169]
	v_lshlrev_b32_e32 v178, 16, v100
	v_and_b32_e32 v179, 0xffff0000, v100
	v_lshlrev_b32_e32 v180, 16, v101
	v_and_b32_e32 v181, 0xffff0000, v101
	v_lshlrev_b32_e32 v182, 16, v102
	v_and_b32_e32 v183, 0xffff0000, v102
	v_pk_fma_f32 v[170:171], v[42:43], v[194:195], v[170:171]
	v_pk_fma_f32 v[66:67], v[36:37], v[178:179], v[66:67]
	v_pk_fma_f32 v[154:155], v[38:39], v[180:181], v[154:155]
	v_pk_fma_f32 v[186:187], v[32:33], v[182:183], v[168:169]
	v_lshlrev_b32_e32 v192, 16, v103
	v_and_b32_e32 v193, 0xffff0000, v103
	v_cvt_pk_bf16_f32 v168, v66, v67
	v_cvt_pk_bf16_f32 v169, v154, v155
	s_and_b64 s[18:19], s[18:19], s[20:21]
	v_pk_fma_f32 v[198:199], v[34:35], v[192:193], v[170:171]
	v_cvt_pk_bf16_f32 v170, v186, v187
	v_pk_fma_f32 v[66:67], v[60:61], v[184:185], v[124:125]
	v_cvt_pk_bf16_f32 v171, v198, v199
	ds_write_b128 v151, v[168:171] offset:1360
	v_pk_fma_f32 v[168:169], v[52:53], v[190:191], v[120:121]
	v_pk_fma_f32 v[60:61], v[60:61], v[172:173], v[124:125]
	v_pk_fma_f32 v[52:53], v[52:53], v[176:177], v[120:121]
	s_waitcnt vmcnt(0)
	v_cndmask_b32_e64 v108, 0, v108, s[18:19]
	v_pk_fma_f32 v[154:155], v[62:63], v[188:189], v[126:127]
	v_pk_fma_f32 v[66:67], v[56:57], v[172:173], v[66:67]
	v_pk_fma_f32 v[168:169], v[44:45], v[176:177], v[168:169]
	v_lshlrev_b32_e32 v184, 16, v104
	v_and_b32_e32 v185, 0xffff0000, v104
	v_lshlrev_b32_e32 v188, 16, v106
	v_and_b32_e32 v189, 0xffff0000, v106
	v_pk_fma_f32 v[62:63], v[62:63], v[174:175], v[126:127]
	v_pk_fma_f32 v[56:57], v[56:57], v[178:179], v[60:61]
	v_pk_fma_f32 v[44:45], v[44:45], v[182:183], v[52:53]
	v_cndmask_b32_e64 v109, 0, v109, s[18:19]
	v_pk_fma_f32 v[154:155], v[58:59], v[174:175], v[154:155]
	v_pk_fma_f32 v[66:67], v[48:49], v[178:179], v[66:67]
	v_pk_fma_f32 v[168:169], v[40:41], v[182:183], v[168:169]
	v_lshlrev_b32_e32 v186, 16, v105
	v_and_b32_e32 v187, 0xffff0000, v105
	v_pk_fma_f32 v[58:59], v[58:59], v[180:181], v[62:63]
	v_pk_fma_f32 v[48:49], v[48:49], v[184:185], v[56:57]
	v_pk_fma_f32 v[40:41], v[40:41], v[188:189], v[44:45]
	v_lshlrev_b32_e32 v44, 16, v108
	v_and_b32_e32 v45, 0xffff0000, v108
	v_cndmask_b32_e64 v110, 0, v110, s[18:19]
	v_pk_fma_f32 v[170:171], v[54:55], v[196:197], v[122:123]
	v_pk_fma_f32 v[154:155], v[50:51], v[180:181], v[154:155]
	v_pk_fma_f32 v[66:67], v[36:37], v[184:185], v[66:67]
	v_pk_fma_f32 v[54:55], v[54:55], v[194:195], v[122:123]
	v_pk_fma_f32 v[50:51], v[50:51], v[186:187], v[58:59]
	v_pk_fma_f32 v[36:37], v[36:37], v[44:45], v[48:49]
	v_lshlrev_b32_e32 v44, 16, v109
	v_and_b32_e32 v45, 0xffff0000, v109
	v_cndmask_b32_e64 v111, 0, v111, s[18:19]
	v_pk_fma_f32 v[170:171], v[46:47], v[194:195], v[170:171]
	v_pk_fma_f32 v[154:155], v[38:39], v[186:187], v[154:155]
	v_lshlrev_b32_e32 v196, 16, v107
	v_and_b32_e32 v197, 0xffff0000, v107
	v_pk_fma_f32 v[46:47], v[46:47], v[192:193], v[54:55]
	v_pk_fma_f32 v[38:39], v[38:39], v[44:45], v[50:51]
	v_lshlrev_b32_e32 v44, 16, v110
	v_and_b32_e32 v45, 0xffff0000, v110
	v_pk_fma_f32 v[170:171], v[42:43], v[192:193], v[170:171]
	v_pk_fma_f32 v[190:191], v[32:33], v[188:189], v[168:169]
	v_pk_fma_f32 v[42:43], v[42:43], v[196:197], v[46:47]
	v_pk_fma_f32 v[40:41], v[32:33], v[44:45], v[40:41]
	v_lshlrev_b32_e32 v32, 16, v111
	v_and_b32_e32 v33, 0xffff0000, v111
	v_pk_fma_f32 v[198:199], v[34:35], v[196:197], v[170:171]
	v_cvt_pk_bf16_f32 v168, v66, v67
	v_cvt_pk_bf16_f32 v169, v154, v155
	v_cvt_pk_bf16_f32 v170, v190, v191
	v_pk_fma_f32 v[42:43], v[34:35], v[32:33], v[42:43]
	v_cvt_pk_bf16_f32 v171, v198, v199
	ds_write_b128 v151, v[168:171] offset:1632
	v_cvt_pk_bf16_f32 v32, v36, v37
	v_cvt_pk_bf16_f32 v33, v38, v39
	v_cvt_pk_bf16_f32 v34, v40, v41
	v_cvt_pk_bf16_f32 v35, v42, v43
	s_cmp_eq_u32 s80, 0x80000
	ds_write_b128 v151, v[32:35] offset:1904
	s_cbranch_scc1 .LBB0_294
	v_lshl_add_u64 v[32:33], v[136:137], 0, s[80:81]
	global_load_dwordx4 v[68:71], v[32:33], off offset:-1280
	global_load_dwordx4 v[72:75], v[32:33], off offset:-1024
	global_load_dwordx4 v[76:79], v[32:33], off offset:-768
	global_load_dwordx4 v[80:83], v[32:33], off offset:-512
	global_load_dwordx4 v[84:87], v[32:33], off offset:-256
	global_load_dwordx4 v[88:91], v[32:33], off
	global_load_dwordx4 v[92:95], v[32:33], off offset:256
	global_load_dwordx4 v[96:99], v[32:33], off offset:512
	global_load_dwordx4 v[100:103], v[32:33], off offset:768
	global_load_dwordx4 v[104:107], v[32:33], off offset:1024
	global_load_dwordx4 v[108:111], v[32:33], off offset:1280
	s_movk_i32 s92, 0x800
	s_mov_b32 s20, s90
	s_branch .LBB0_295

; #define LAS __attribute__((address_space(3)))
; template <int dir>
; __device__ __forceinline__ void lru_pass(LAS unsigned char* lds, const Params& P, int b, int h, int q, bool dry) {
;     ...
;             if (sc >= 2) {
;                 if (dir == 0) {
; #pragma unroll
;                     for (int i = 0; i < 4; ++i) { const int id = tid + i * NTHREADS; *(u32x4*)(Hg + (size_t)(t0_prev + (id >> 3)) * DM + (id & 7) * 4) = *(const LAS u32x4*)(TOUT + (id >> 3) * IO_WP + (id & 7) * 16); }
.LBB0_295:
	s_waitcnt lgkmcnt(0)
	s_barrier
	s_setprio 0
	s_cmp_lt_u32 s93, 2
	s_cbranch_scc1 .LBB0_297
	s_add_u32 s18, s80, 0x5fe0000
	s_addc_u32 s19, s81, 0
	ds_read_b128 v[32:35], v158
	ds_read_b128 v[36:39], v159
	v_lshl_add_u64 v[48:49], v[134:135], 0, s[18:19]
	v_lshl_add_u64 v[50:51], v[132:133], 0, s[18:19]
	s_waitcnt lgkmcnt(1)
	global_store_dwordx4 v[48:49], v[32:35], off
	s_waitcnt lgkmcnt(0)
	global_store_dwordx4 v[50:51], v[36:39], off

; #define LAS __attribute__((address_space(3)))
; __device__ __forceinline__ unsigned cvt_pk_bf16(float lo, float hi) { unsigned r; asm volatile("v_cvt_pk_bf16_f32 %0, %1, %2" : "=v"(r) : "v"(lo), "v"(hi)); return r; }
; __device__ __forceinline__ float bf_lo(unsigned u) { return __uint_as_float(u << 16); }
; __device__ __forceinline__ float bf_hi(unsigned u) { return __uint_as_float(u & 0xffff0000u); }
; __device__ __forceinline__ bf16_t f2bf(float f) { return (bf16_t)(cvt_pk_bf16(f, 0.f) & 0xffffu); }
; #define LDS_BARRIER() do { asm volatile("s_waitcnt lgkmcnt(0)" ::: "memory"); __builtin_amdgcn_s_barrier(); asm volatile("" ::: "memory"); } while (0)
; template <int dir>
; __device__ __forceinline__ void lru_pass(LAS unsigned char* lds, const Params& P, int b, int h, int q, bool dry) {
;     ...
;             const float Po = __shfl_xor(Pp, 32), Eo = __shfl_xor(E, 32);
;             const float P0 = g ? Po : Pp, E0 = g ? Eo : E, P1 = g ? Pp : Po, E1 = g ? E : Eo;
;             if (g == 0) { AGG[(wid * 2 + 0) * 32 + nl] = P0 * P1; AGG[(wid * 2 + 1) * 32 + nl] = fmaf(P1, E0, E1); }
;             LDS_BARRIER();
;             float cin = carry, cend = carry;
; #pragma unroll
;             for (int w = 0; w < 8; ++w) { const float pw = AGG[(w * 2 + 0) * 32 + nl], ew = AGG[(w * 2 + 1) * 32 + nl]; if (w == wid) cin = cend; cend = fmaf(pw, cend, ew); }
;             carry = cend;
;             if (g) cin = fmaf(P0, cin, E0);
;             if (!isctx) {
; #pragma unroll
;                 for (int v = 0; v < 16; ++v) { const float hv = fmaf(zi[v], cin, zr[v]);
;                     const int s = sbase + v; const int tl = dir == 0 ? s : 255 - s;
;                     if (dir == 0) *(LAS unsigned*)(TOUT + tl * IO_WP + nl * 4) = (cvt_pk_bf16(hv, 0.f) & 0xffffu) | (pk[v] << 16);
;                     else *(LAS bf16_t*)(TOUT + tl * IO_NP + nl * 2) = f2bf((bf_lo(pk[v]) + hv) * bf_hi(pk[v])); }
.LBB0_299:
	s_or_b64 exec, exec, s[18:19]
	s_waitcnt lgkmcnt(0)
	s_barrier
	s_setprio 1
	v_add_u32_e32 v34, s99, v140
	ds_read2_b32 v[36:37], v34 offset1:32
	ds_read2_b32 v[38:39], v34 offset0:64 offset1:96
	ds_read2_b32 v[40:41], v34 offset0:128 offset1:160
	ds_read2_b32 v[42:43], v34 offset0:192 offset1:224
	v_add_u32_e32 v32, s100, v140
	ds_read2_b32 v[44:45], v32 offset1:32
	s_waitcnt lgkmcnt(4)
	v_fmac_f32_e32 v37, v36, v165
	ds_read2_b32 v[46:47], v32 offset0:64 offset1:96
	s_waitcnt lgkmcnt(4)
	v_fmac_f32_e32 v39, v38, v37
	ds_read2_b32 v[34:35], v32 offset0:128 offset1:160
	s_waitcnt lgkmcnt(4)
	v_fmac_f32_e32 v41, v40, v39
	ds_read2_b32 v[32:33], v32 offset0:192 offset1:224
	s_waitcnt lgkmcnt(4)
	v_fmac_f32_e32 v43, v42, v41
	s_waitcnt lgkmcnt(3)
	v_fmac_f32_e32 v45, v44, v43
	s_waitcnt lgkmcnt(2)
	v_fmac_f32_e32 v47, v46, v45
	s_cmp_eq_u32 s80, 0
	s_waitcnt lgkmcnt(1)
	v_fmac_f32_e32 v35, v34, v47
	s_cbranch_scc1 .LBB0_301
	v_cndmask_b32_e64 v37, v165, v37, s[14:15]
	v_cndmask_b32_e64 v37, v37, v39, s[12:13]
	v_cndmask_b32_e64 v37, v37, v41, s[10:11]
	v_cndmask_b32_e64 v37, v37, v43, s[8:9]
	v_cndmask_b32_e64 v37, v37, v45, s[4:5]
	v_cndmask_b32_e64 v37, v37, v47, s[16:17]
	v_cndmask_b32_e32 v34, v188, v187, vcc
	v_cndmask_b32_e32 v36, v189, v185, vcc
	v_cndmask_b32_e64 v37, v37, v35, s[0:1]
	v_fmac_f32_e32 v36, v34, v37
	v_cndmask_b32_e32 v34, v36, v37, vcc
	v_fmac_f32_e32 v49, v171, v34
	v_fmac_f32_e32 v172, v50, v34
	v_fmac_f32_e32 v173, v51, v34
	v_fmac_f32_e32 v174, v52, v34
	v_fmac_f32_e32 v175, v53, v34
	v_fmac_f32_e32 v176, v54, v34
	v_fmac_f32_e32 v177, v55, v34
	v_fmac_f32_e32 v178, v56, v34
	v_fmac_f32_e32 v179, v57, v34
	v_fmac_f32_e32 v180, v58, v34
	v_fmac_f32_e32 v181, v59, v34
	v_fmac_f32_e32 v182, v60, v34
	v_fmac_f32_e32 v183, v61, v34
	v_fmac_f32_e32 v184, v62, v34
	v_fmac_f32_e32 v63, v186, v34
	v_fmac_f32_e32 v185, v187, v34
	v_cvt_pk_bf16_f32 v36, v49, v172
	ds_write_b16 v164, v36
	ds_write_b16_d16_hi v164, v36 offset:80
	v_cvt_pk_bf16_f32 v37, v173, v174
	ds_write_b16 v164, v37 offset:160
	ds_write_b16_d16_hi v164, v37 offset:240
	v_cvt_pk_bf16_f32 v38, v175, v176
	ds_write_b16 v164, v38 offset:320
	ds_write_b16_d16_hi v164, v38 offset:400
	v_cvt_pk_bf16_f32 v39, v177, v178
	ds_write_b16 v164, v39 offset:480
	ds_write_b16_d16_hi v164, v39 offset:560
	v_cvt_pk_bf16_f32 v36, v179, v180
	ds_write_b16 v164, v36 offset:640
	ds_write_b16_d16_hi v164, v36 offset:720
	v_cvt_pk_bf16_f32 v37, v181, v182
	ds_write_b16 v164, v37 offset:800
	ds_write_b16_d16_hi v164, v37 offset:880
	v_cvt_pk_bf16_f32 v38, v183, v184
	ds_write_b16 v164, v38 offset:960
	ds_write_b16_d16_hi v164, v38 offset:1040
	v_cvt_pk_bf16_f32 v39, v63, v185
	ds_write_b16 v164, v39 offset:1120
	ds_write_b16_d16_hi v164, v39 offset:1200

; #define LAS __attribute__((address_space(3)))
; __device__ __forceinline__ int opaque_tid() { int t = threadIdx.x; asm volatile("" : "+v"(t)); return t; }
; template <int dir>
; __device__ __forceinline__ void lru_pass(LAS unsigned char* lds, const Params& P, int b, int h, int q, bool dry) {
;     const int tid = opaque_tid(), lane = tid & 63, wid = __builtin_amdgcn_readfirstlane(tid >> 6), g = lane >> 5, nl = lane & 31;
;     const int chl = q * 32 + nl, ch = h * 128 + chl;
;     LAS unsigned char* XC = lds;
;     LAS float* AGG = (LAS float*)(lds + 256 * XC_PITCH);
;     LAS unsigned char* WB = lds + 256 * XC_PITCH + 2048;
;     LAS float* CWL = (LAS float*)(lds + 256 * XC_PITCH + 2048 + 64 * XC_PITCH);
;     LAS unsigned char* TIN = lds + LRU_IO_OFF;
;     LAS unsigned char* TOUT = lds + LRU_IO_OFF + 256 * (dir == 0 ? IO_NP : IO_WP);
;     bf16_t* Z = (bf16_t*)(P.ws + WS_Z); const bf16_t* ZC = (const bf16_t*)(P.ws + WS_ZC); unsigned* HFW = (unsigned*)(P.ws + WS_HF);
;     const bf16_t* LruW = (const bf16_t*)(P.ws + WS_LRUW);
;     const int cgp = tid & 15, tr = tid >> 4;
;     const int s_i = 16 * ((nl >> 2) & 1) + ((nl >> 3) << 2) + (nl & 3);
;     const bf16_t* Zg = Z + ZSLAB(8 + h, (size_t)b * SEQ) + q * 32;
;     unsigned* Hg = HFW + (size_t)b * SEQ * DM + h * 128 + q * 32;
;     {
; #pragma unroll
;         for (int i = 0; i < 2; ++i) { const int idx = tid + i * NTHREADS, gate = idx >> 9, n = (idx >> 4) & 31, kc = idx & 15;
;             *(LAS u32x4*)(WB + (gate * 32 + n) * XC_PITCH + kc * 16) = *(const u32x4*)(LruW + ((size_t)((dir * 2 + gate) * 8 + h) * 128 + q * 32 + n) * 128 + kc * 8); }
;         const float br = -LOG2E * P.lru_ba[(dir * 8 + h) * 128 + chl], bi = -LOG2E * P.lru_bx[(dir * 8 + h) * 128 + chl];
;         const float lam = P.lru_lambda[dir * 1024 + ch];
;         const float cl = -8.0f * LOG2E * log1pf(__expf(-lam));
;         float carry = 0.f;
;         LruTile cur = lru_tile(Z, ZC, b, h, dir, 0);
;         u32x4 rows[11];
;         constexpr int NIN = dir == 0 ? 2 : 4;
;         u32x4 inr[NIN];
;         lru_load_rows(rows, cur, tr, cgp);
;     ...
;         if (dir == 0) {
; #pragma unroll
;             for (int i = 0; i < 4; ++i) { const int id = tid + i * NTHREADS; *(u32x4*)(Hg + (size_t)(t0_prev + (id >> 3)) * DM + (id & 7) * 4) = *(const LAS u32x4*)(TOUT + (id >> 3) * IO_WP + (id & 7) * 16); }
.Lpp_f_noy:
	s_waitcnt lgkmcnt(0)
	s_barrier
	s_add_u32 s18, s80, 0x5fe0000
	s_addc_u32 s19, s81, 0
	ds_read_b128 v[0:3], v158
	ds_read_b128 v[4:7], v159
	v_lshl_add_u64 v[8:9], v[134:135], 0, s[18:19]
	v_lshl_add_u64 v[10:11], v[132:133], 0, s[18:19]
	s_waitcnt lgkmcnt(1)
	global_store_dwordx4 v[8:9], v[0:3], off
	s_waitcnt lgkmcnt(0)
	global_store_dwordx4 v[10:11], v[4:7], off
	s_waitcnt lgkmcnt(0)
	v_mov_b32_e32 v32, v167
	s_barrier
	s_or_b32 s0, s26, 16
	v_and_b32_e32 v15, 31, v32
	v_or_b32_e32 v17, s28, v15
	v_add_u32_e32 v13, 0x200, v32
	v_or_b32_e32 v8, s27, v17
	v_ashrrev_i32_e32 v11, 9, v32
	v_ashrrev_i32_e32 v14, 9, v13
	v_lshlrev_b32_e32 v8, 2, v8
	v_mov_b32_e32 v9, v65
	v_lshl_add_u32 v2, v11, 3, s0
	v_lshl_add_u32 v6, v14, 3, s0
	v_lshl_add_u64 v[8:9], s[64:65], 0, v[8:9]
	s_movk_i32 s0, 0x1000
	v_add_co_u32_e32 v8, vcc, s0, v8
	v_and_b32_e32 v12, 15, v32
	s_nop 0
	v_addc_co_u32_e32 v9, vcc, 0, v9, vcc
	global_load_dword v16, v[8:9], off
	v_bfe_u32 v10, v32, 4, 5
	v_lshlrev_b32_e32 v64, 4, v12
	v_ashrrev_i32_e32 v3, 31, v2
	v_ashrrev_i32_e32 v7, 31, v6
	v_or_b32_e32 v4, s28, v10
	v_lshl_add_u64 v[0:1], s[38:39], 0, v[64:65]
	v_lshlrev_b64 v[2:3], 15, v[2:3]
	v_lshlrev_b64 v[6:7], 15, v[6:7]
	v_lshlrev_b32_e32 v4, 8, v4
	v_mov_b32_e32 v5, v65
	v_lshl_add_u64 v[2:3], v[0:1], 0, v[2:3]
	v_lshl_add_u64 v[0:1], v[0:1], 0, v[6:7]
	v_lshl_add_u64 v[2:3], v[2:3], 0, v[4:5]
	v_lshl_add_u64 v[4:5], v[0:1], 0, v[4:5]
	global_load_dwordx4 v[0:3], v[2:3], off
	s_nop 0
	global_load_dwordx4 v[4:7], v[4:5], off
	v_lshrrev_b32_e32 v8, 1, v32
	v_lshlrev_b32_e32 v9, 2, v32
	v_and_b32_e32 v20, 12, v8
	v_lshl_or_b32 v11, v11, 5, v10
	v_add_u32_e32 v8, s88, v64
	v_lshl_or_b32 v14, v14, 5, v10
	v_mad_u64_u32 v[10:11], s[6:7], v11, s89, v[8:9]
	s_or_b32 s8, s26, 8
	v_and_or_b32 v20, v9, 16, v20
	v_lshlrev_b32_e32 v21, 2, v17
	v_mad_u64_u32 v[8:9], s[6:7], v14, s89, v[8:9]
	v_lshl_or_b32 v9, s8, 9, v21
	global_load_dword v14, v9, s[58:59]
	s_nop 0
	global_load_dword v9, v9, s[62:63]
	s_mov_b32 s80, 0x3f2aaaab
	s_mov_b32 s81, 0x3f317218
	s_mov_b32 s91, 0x7f800000
	s_mov_b32 s92, 0x33800000
	v_ashrrev_i32_e32 v33, 4, v32
	v_lshlrev_b32_e32 v34, 3, v12
	v_readfirstlane_b32 s4, v32
	s_lshl_b64 s[0:1], s[78:79], 11
	s_lshl_b32 s5, s8, 14
	s_ashr_i32 s6, s4, 6
	s_add_u32 s26, s0, s5
	s_addc_u32 s27, s1, 0
	s_lshl_b32 s0, s28, 1
	v_readlane_b32 s1, v255, 10
	v_and_b32_e32 v19, 3, v32
	s_add_u32 s0, s1, s0
	v_bfe_u32 v18, v32, 5, 1
	v_add_u32_e32 v44, 0, v64
	v_lshlrev_b32_e32 v64, 4, v19
	s_addc_u32 s1, s3, 0
	v_lshl_add_u64 v[136:137], s[0:1], 0, v[64:65]
	s_lshl_b32 s0, s6, 5
	v_lshlrev_b32_e32 v46, 4, v18
	v_or_b32_e32 v37, s0, v46
	v_add_u32_e32 v158, s86, v64
	v_or_b32_e32 v64, 4, v37
	s_movk_i32 s93, 0x880
	v_ashrrev_i32_e32 v36, 3, v32
	v_ashrrev_i32_e32 v38, 3, v13
	v_ashrrev_i32_e32 v140, 2, v32
	v_sub_u32_e32 v39, 0xff, v37
	v_sub_u32_e32 v64, 0xff, v64
	v_lshl_add_u32 v160, v33, 3, -1
	v_mul_lo_u32 v52, v33, s93
	v_lshl_or_b32 v110, v33, 13, v34
	v_mov_b32_e32 v111, v65
	v_lshlrev_b64 v[110:111], 1, v[110:111]
	v_lshl_add_u64 v[108:109], s[48:49], 0, v[110:111]
	global_load_dwordx4 v[68:71], v[108:109], off offset:-2048
	global_load_dwordx4 v[72:75], v[108:109], off
	global_load_dwordx4 v[76:79], v[108:109], off offset:2048
	v_lshl_add_u64 v[108:109], s[50:51], 0, v[110:111]
	global_load_dwordx4 v[80:83], v[108:109], off
	v_lshl_add_u64 v[108:109], s[56:57], 0, v[110:111]
	global_load_dwordx4 v[84:87], v[108:109], off
	v_lshl_add_u64 v[108:109], s[60:61], 0, v[110:111]
	global_load_dwordx4 v[88:91], v[108:109], off
	v_lshl_add_u64 v[108:109], s[66:67], 0, v[110:111]
	global_load_dwordx4 v[92:95], v[108:109], off
	v_lshl_add_u64 v[108:109], s[70:71], 0, v[110:111]
	global_load_dwordx4 v[96:99], v[108:109], off
	v_lshl_add_u64 v[108:109], s[72:73], 0, v[110:111]
	global_load_dwordx4 v[100:103], v[108:109], off
	v_lshl_add_u64 v[108:109], s[74:75], 0, v[110:111]
	global_load_dwordx4 v[104:107], v[108:109], off
	v_lshl_add_u64 v[108:109], s[76:77], 0, v[110:111]
	global_load_dwordx4 v[108:111], v[108:109], off
	s_waitcnt vmcnt(14)
	ds_write_b128 v10, v[0:3]
	s_waitcnt vmcnt(13)
	ds_write_b128 v8, v[4:7]
	v_mul_f32_e32 v11, 0xbfb8aa3b, v16
	v_exp_f32_e32 v11, v11
	v_mul_lo_u32 v57, v39, s89
	v_mul_lo_u32 v58, v39, s30
	v_mul_lo_u32 v114, v64, s89
	v_add_f32_e32 v2, 1.0, v11
	v_add_f32_e32 v3, -1.0, v2
	v_frexp_mant_f32_e32 v4, v2
	v_cvt_f64_f32_e32 v[0:1], v2
	v_sub_f32_e32 v5, v3, v2
	v_frexp_exp_i32_f64_e32 v0, v[0:1]
	v_cmp_gt_f32_e32 vcc, s80, v4
	v_sub_f32_e32 v3, v11, v3
	v_add_f32_e32 v1, 1.0, v5
	v_subbrev_co_u32_e32 v0, vcc, 0, v0, vcc
	v_add_f32_e32 v1, v3, v1
	v_sub_u32_e32 v3, 0, v0
	v_ldexp_f32 v2, v2, v3
	v_ldexp_f32 v1, v1, v3
	v_add_f32_e32 v3, -1.0, v2
	v_add_f32_e32 v4, 1.0, v2
	v_add_f32_e32 v5, 1.0, v3
	v_add_f32_e32 v6, -1.0, v4
	v_sub_f32_e32 v5, v2, v5
	v_sub_f32_e32 v2, v2, v6
	v_add_f32_e32 v5, v1, v5
	v_add_f32_e32 v1, v1, v2
	v_add_f32_e32 v7, v4, v1
	v_rcp_f32_e32 v8, v7
	v_add_f32_e32 v2, v3, v5
	v_sub_f32_e32 v4, v7, v4
	v_sub_f32_e32 v3, v2, v3
	v_sub_f32_e32 v1, v1, v4
	v_mul_f32_e32 v4, v2, v8
	v_sub_f32_e32 v3, v5, v3
	v_mul_f32_e32 v5, v7, v4
	v_fma_f32 v10, v4, v7, -v5
	v_fmac_f32_e32 v10, v4, v1
	v_add_f32_e32 v16, v5, v10
	v_sub_f32_e32 v21, v2, v16
	v_sub_f32_e32 v2, v2, v21
	v_sub_f32_e32 v5, v16, v5
	v_sub_f32_e32 v2, v2, v16
	v_sub_f32_e32 v5, v5, v10
	v_add_f32_e32 v2, v3, v2
	v_add_f32_e32 v2, v5, v2
	v_add_f32_e32 v3, v21, v2
	v_mul_f32_e32 v5, v8, v3
	v_sub_f32_e32 v10, v21, v3
	v_mul_f32_e32 v16, v7, v5
	v_add_f32_e32 v2, v2, v10
	v_add_f32_e32 v10, v4, v5
	v_fma_f32 v7, v5, v7, -v16
	v_sub_f32_e32 v4, v10, v4
; template <int dir>
; __device__ __forceinline__ void lru_pass(LAS unsigned char* lds, const Params& P, int b, int h, int q, bool dry) {
;     ...
;         const float br = -LOG2E * P.lru_ba[(dir * 8 + h) * 128 + chl], bi = -LOG2E * P.lru_bx[(dir * 8 + h) * 128 + chl];
;         const float lam = P.lru_lambda[dir * 1024 + ch];
;         const float cl = -8.0f * LOG2E * log1pf(__expf(-lam));
;         float carry = 0.f;
;         LruTile cur = lru_tile(Z, ZC, b, h, dir, 0);
;         u32x4 rows[11];
;         constexpr int NIN = dir == 0 ? 2 : 4;
;         u32x4 inr[NIN];
;         lru_load_rows(rows, cur, tr, cgp);
;     ...
;             const int sbase = 32 * wid + 16 * g;
;             { const int sl = 32 * wid + s_i; const int tlA = dir == 0 ? sl : 255 - sl;
;               const LAS unsigned char* ap = XC + tlA * XC_PITCH + 16 * g;
;               const LAS unsigned char* wrp = WB + nl * XC_PITCH + 16 * g; const LAS unsigned char* wip = wrp + 32 * XC_PITCH;
; #pragma unroll
;               for (int ks = 0; ks < 8; ++ks) { const bf16x8 A = *(const LAS bf16x8*)(ap + 32 * ks);
;                   const bf16x8 Br = *(const LAS bf16x8*)(wrp + 32 * ks), Bi = *(const LAS bf16x8*)(wip + 32 * ks);
;                   zr = __builtin_amdgcn_mfma_f32_32x32x16_bf16(A, Br, zr, 0, 0, 0); zi = __builtin_amdgcn_mfma_f32_32x32x16_bf16(A, Bi, zi, 0, 0, 0); } }
;             unsigned xcb[16], pk[16];
; #pragma unroll
;             for (int v = 0; v < 16; ++v) { const int s = sbase + v; const int tl = dir == 0 ? s : 255 - s; xcb[v] = *(const LAS bf16_t*)(XC + tl * XC_PITCH + chl * 2);
;                 if (dir == 0) pk[v] = *(const LAS bf16_t*)(TIN + tl * IO_NP + nl * 2); else pk[v] = *(const LAS unsigned*)(TIN + tl * IO_WP + nl * 4); }
;             float Pp = 1.f, E = 0.f;
; #pragma unroll
;             for (int v = 0; v < 16; ++v) {
;                 const float xcv = __uint_as_float(xcb[v] << 16);
;                 const float r = __builtin_amdgcn_rcpf(1.0f + __builtin_amdgcn_exp2f(zr[v]));
;                 const float ig = __builtin_amdgcn_rcpf(1.0f + __builtin_amdgcn_exp2f(zi[v]));
;                 const float a = __builtin_amdgcn_exp2f(cl * r);
;                 const float sq = __builtin_amdgcn_sqrtf(fmaf(-a, a, 1.0f));
;                 const float u = sq * ig * xcv;
;                 E = fmaf(a, E, u); Pp *= a; zr[v] = E; zi[v] = Pp; }
	v_fmac_f32_e32 v7, v5, v1
	v_sub_f32_e32 v1, v5, v4
	v_add_f32_e32 v4, v16, v7
	v_sub_f32_e32 v5, v4, v16
	v_sub_f32_e32 v16, v3, v4
	v_sub_f32_e32 v3, v3, v16
	v_sub_f32_e32 v3, v3, v4
	v_cvt_f32_i32_e32 v0, v0
	v_sub_f32_e32 v5, v5, v7
	v_add_f32_e32 v2, v2, v3
	v_add_f32_e32 v2, v5, v2
	v_add_f32_e32 v2, v16, v2
	v_mul_f32_e32 v2, v8, v2
	v_mul_f32_e32 v6, 0x3f317218, v0
	v_add_f32_e32 v1, v1, v2
	v_add_f32_e32 v2, v10, v1
	v_fma_f32 v5, v0, s81, -v6
	v_fmac_f32_e32 v5, 0xb102e308, v0
	v_sub_f32_e32 v0, v2, v10
	v_mul_f32_e32 v3, v2, v2
	v_sub_f32_e32 v0, v1, v0
	v_add_f32_e32 v1, v6, v5
	v_fmamk_f32 v4, v3, 0x3e9b6dac, v200
	v_sub_f32_e32 v6, v1, v6
	v_fmaak_f32 v4, v3, v4, 0x3f2aaada
	v_sub_f32_e32 v5, v5, v6
	v_ldexp_f32 v6, v2, 1
	v_mul_f32_e32 v2, v2, v3
	v_mul_f32_e32 v2, v2, v4
	v_add_f32_e32 v3, v6, v2
	v_sub_f32_e32 v4, v3, v6
	v_ldexp_f32 v0, v0, 1
	v_sub_f32_e32 v2, v2, v4
	v_add_f32_e32 v0, v0, v2
	v_add_f32_e32 v2, v3, v0
	v_sub_f32_e32 v3, v2, v3
	v_sub_f32_e32 v0, v0, v3
	v_add_f32_e32 v3, v1, v2
	v_sub_f32_e32 v4, v3, v1
	v_sub_f32_e32 v6, v3, v4
	v_sub_f32_e32 v1, v1, v6
	v_sub_f32_e32 v2, v2, v4
	v_add_f32_e32 v1, v2, v1
	v_add_f32_e32 v2, v5, v0
	v_sub_f32_e32 v4, v2, v5
	v_add_f32_e32 v1, v2, v1
	v_sub_f32_e32 v6, v2, v4
	v_add_f32_e32 v2, v3, v1
	v_sub_f32_e32 v5, v5, v6
	v_sub_f32_e32 v0, v0, v4
	v_sub_f32_e32 v3, v2, v3
	v_add_f32_e32 v0, v0, v5
	v_sub_f32_e32 v1, v1, v3
	v_add_f32_e32 v0, v0, v1
	v_add_f32_e32 v0, v2, v0
	v_cmp_neq_f32_e32 vcc, s91, v11
	v_mov_b32_e32 v1, v65
	v_mul_lo_u32 v115, v64, s30
	v_cndmask_b32_e32 v0, v201, v0, vcc
	v_cmp_ngt_f32_e32 vcc, -1.0, v11
	v_mul_lo_u32 v206, v39, s87
	v_mul_lo_u32 v210, v64, s87
	v_cndmask_b32_e32 v0, v202, v0, vcc
	v_cmp_neq_f32_e32 vcc, -1.0, v11
	v_ashrrev_i32_e32 v39, 31, v38
	v_sub_u32_e32 v41, 0xfe, v37
	v_cndmask_b32_e32 v0, v203, v0, vcc
	v_cmp_lt_f32_e64 vcc, |v11|, s92
	v_mul_lo_u32 v59, v41, s89
	v_mul_lo_u32 v60, v41, s30
	v_cndmask_b32_e32 v6, v0, v11, vcc
	v_lshlrev_b32_e32 v2, 4, v32
	v_and_b32_e32 v2, 0x70, v2
	v_lshlrev_b32_e32 v1, 2, v15
	v_add_u32_e32 v45, s95, v2
	v_or3_b32 v2, v19, v20, s0
	s_and_b32 s0, s4, 0x3fffffc0
	v_add_u32_e32 v161, s94, v1
	s_cmp_eq_u32 s6, 7
	v_lshl_add_u32 v254, s0, 2, v161
	s_cselect_b64 s[0:1], -1, 0
	s_cmp_eq_u32 s6, 6
	s_cselect_b64 s[16:17], -1, 0
	s_cmp_eq_u32 s6, 5
	s_cselect_b64 s[4:5], -1, 0
	s_cmp_eq_u32 s6, 4
	s_cselect_b64 s[8:9], -1, 0
	s_cmp_eq_u32 s6, 3
	s_cselect_b64 s[10:11], -1, 0
	s_cmp_eq_u32 s6, 2
	s_cselect_b64 s[12:13], -1, 0
	s_cmp_eq_u32 s6, 1
	s_cselect_b64 s[14:15], -1, 0
	s_lshl_b32 s6, s25, 7
	s_and_b32 s6, s6, 0xe00
	s_lshl_b32 s7, s29, 7
	s_or_b32 s6, s7, s6
	s_add_u32 s6, s6, s44
	v_add_u32_e32 v50, s95, v1
	v_add_u32_e32 v1, 0x400, v32
	s_addc_u32 s7, 0, s45
	v_ashrrev_i32_e32 v40, 3, v1
	v_add_u32_e32 v1, 0x600, v32
	v_and_b32_e32 v32, 7, v32
	s_add_u32 s18, s84, s46
	v_lshlrev_b32_e32 v64, 4, v32
	v_lshl_or_b32 v32, v33, 10, v34
	v_mov_b32_e32 v33, v65
	s_addc_u32 s19, s85, s47
	v_lshl_add_u64 v[144:145], v[32:33], 1, s[18:19]
	v_lshlrev_b64 v[32:33], 12, v[38:39]
	v_lshl_add_u64 v[32:33], s[6:7], 0, v[32:33]
	v_mul_lo_u32 v207, v41, s87
	v_lshl_add_u64 v[32:33], v[32:33], 0, v[64:65]
	v_ashrrev_i32_e32 v41, 31, v40
	v_or_b32_e32 v43, 2, v37
	v_lshl_add_u64 v[252:253], s[42:43], 0, v[32:33]
	v_lshlrev_b64 v[32:33], 12, v[40:41]
	v_ashrrev_i32_e32 v42, 3, v1
	v_sub_u32_e32 v43, 0xff, v43
	v_or_b32_e32 v63, 3, v37
	v_or_b32_e32 v66, 5, v37
	v_or_b32_e32 v67, 6, v37
	v_or_b32_e32 v120, 7, v37
	v_or_b32_e32 v123, 8, v37
	v_or_b32_e32 v126, 9, v37
	v_or_b32_e32 v129, 10, v37
	v_or_b32_e32 v132, 11, v37
	v_or_b32_e32 v135, 12, v37
	v_or_b32_e32 v142, 13, v37
	v_or_b32_e32 v143, 14, v37
	v_or_b32_e32 v37, 15, v37
	v_lshl_add_u64 v[32:33], s[6:7], 0, v[32:33]
	v_mul_lo_u32 v61, v43, s89
	v_mul_lo_u32 v62, v43, s30
	v_sub_u32_e32 v37, 0xff, v37
	v_mul_lo_u32 v208, v43, s87
	v_lshl_add_u64 v[32:33], v[32:33], 0, v[64:65]
	v_ashrrev_i32_e32 v43, 31, v42
	v_sub_u32_e32 v2, 0xff, v2
	v_mul_lo_u32 v204, v37, s89
	v_mul_lo_u32 v205, v37, s30
	v_mul_lo_u32 v221, v37, s87
	v_ashrrev_i32_e32 v37, 31, v36
	v_lshl_add_u64 v[154:155], s[42:43], 0, v[32:33]
	v_lshlrev_b64 v[32:33], 12, v[42:43]
	v_mul_lo_u32 v2, v2, s89
	v_mul_lo_u32 v53, v36, s30
	v_sub_u32_e32 v63, 0xff, v63
	v_sub_u32_e32 v66, 0xff, v66
	v_sub_u32_e32 v67, 0xff, v67
	v_sub_u32_e32 v120, 0xff, v120
	v_sub_u32_e32 v123, 0xff, v123
	v_sub_u32_e32 v126, 0xff, v126
	v_lshlrev_b64 v[36:37], 12, v[36:37]
	v_lshl_add_u64 v[32:33], s[6:7], 0, v[32:33]
	v_lshlrev_b32_e32 v35, 5, v12
	v_add_u32_e32 v47, 0, v2
	v_mov_b32_e32 v2, s88
	v_lshl_add_u32 v49, v17, 1, 0
	v_lshl_add_u32 v51, v15, 1, s86
	v_mul_lo_u32 v112, v63, s89
	v_mul_lo_u32 v113, v63, s30
	v_mul_lo_u32 v116, v66, s89
	v_mul_lo_u32 v117, v66, s30
	v_mul_lo_u32 v118, v67, s89
	v_mul_lo_u32 v119, v67, s30
	v_mul_lo_u32 v121, v120, s89
	v_mul_lo_u32 v122, v120, s30
	v_mul_lo_u32 v124, v123, s89
	v_mul_lo_u32 v125, v123, s30
	v_mul_lo_u32 v127, v126, s89
	v_mul_lo_u32 v128, v126, s30
	v_sub_u32_e32 v129, 0xff, v129
	v_sub_u32_e32 v132, 0xff, v132
	v_sub_u32_e32 v135, 0xff, v135
	v_sub_u32_e32 v142, 0xff, v142
	v_sub_u32_e32 v143, 0xff, v143
	v_mul_lo_u32 v211, v66, s87
	v_mul_lo_u32 v212, v67, s87
	v_mul_lo_u32 v120, v120, s87
	v_mul_lo_u32 v123, v123, s87
	v_mul_lo_u32 v126, v126, s87
	v_lshl_add_u64 v[36:37], s[6:7], 0, v[36:37]
	v_lshl_add_u64 v[32:33], v[32:33], 0, v[64:65]
	v_mov_b32_e32 v66, v65
	v_mov_b32_e32 v67, v65
	s_waitcnt vmcnt(12)
	v_mul_f32_e32 v0, 0xbfb8aa3b, v14
	s_waitcnt vmcnt(11)
; #define LAS __attribute__((address_space(3)))
; template <int dir>
; __device__ __forceinline__ void lru_pass(LAS unsigned char* lds, const Params& P, int b, int h, int q, bool dry) {
;     ...
;         const float br = -LOG2E * P.lru_ba[(dir * 8 + h) * 128 + chl], bi = -LOG2E * P.lru_bx[(dir * 8 + h) * 128 + chl];
;         const float lam = P.lru_lambda[dir * 1024 + ch];
;         const float cl = -8.0f * LOG2E * log1pf(__expf(-lam));
;         float carry = 0.f;
;         LruTile cur = lru_tile(Z, ZC, b, h, dir, 0);
;         u32x4 rows[11];
;         constexpr int NIN = dir == 0 ? 2 : 4;
;         u32x4 inr[NIN];
;         lru_load_rows(rows, cur, tr, cgp);
; #pragma unroll
;         for (int i = 0; i < NIN; ++i) inr[i] = (u32x4){0u, 0u, 0u, 0u};
;         int t0_prev = 0;
;         for (int sc = 0; sc < 9; ++sc) {
;             const bool isctx = (sc == 0);
;             const int t0 = cur.t0;
; #pragma unroll
;             for (int j = 0; j < 11; ++j) { if (j != 0 && j < 9) continue;
;                 const int t = t0 + tr * 8 - 1 + j; if (t < 0 || t >= cur.L) rows[j] = (u32x4){0u, 0u, 0u, 0u}; }
;             f32x2 cw2[4][4], cb2[4];
; #pragma unroll
;             for (int k = 0; k < 5; ++k) { const f32x4 a = *(const LAS f32x4*)(CWL + k * 128 + cgp * 8), c2 = *(const LAS f32x4*)(CWL + k * 128 + cgp * 8 + 4);
;                 if (k < 4) { cw2[k][0] = (f32x2){a[0], a[1]}; cw2[k][1] = (f32x2){a[2], a[3]}; cw2[k][2] = (f32x2){c2[0], c2[1]}; cw2[k][3] = (f32x2){c2[2], c2[3]}; }
;                 else { cb2[0] = (f32x2){a[0], a[1]}; cb2[1] = (f32x2){a[2], a[3]}; cb2[2] = (f32x2){c2[0], c2[1]}; cb2[3] = (f32x2){c2[2], c2[3]}; } }
	v_mul_f32_e32 v16, 0xbfb8aa3b, v9
	v_mad_u32_u24 v48, v15, s89, v2
	v_mul_lo_u32 v54, v38, s30
	v_mul_lo_u32 v55, v40, s30
	v_mul_lo_u32 v56, v42, s30
	v_ashrrev_i32_e32 v138, 2, v13
	v_mul_lo_u32 v130, v129, s89
	v_mul_lo_u32 v131, v129, s30
	v_mul_lo_u32 v133, v132, s89
	v_mul_lo_u32 v134, v132, s30
	v_mul_lo_u32 v146, v135, s89
	v_mul_lo_u32 v147, v135, s30
	v_mul_lo_u32 v148, v142, s89
	v_mul_lo_u32 v149, v142, s30
	v_mul_lo_u32 v162, v143, s89
	v_mul_lo_u32 v163, v143, s30
	v_mul_lo_u32 v63, v63, s87
	v_mul_lo_u32 v129, v129, s87
	v_mul_lo_u32 v132, v132, s87
	v_mul_lo_u32 v135, v135, s87
	v_mul_lo_u32 v219, v142, s87
	v_mul_lo_u32 v220, v143, s87
	v_lshl_add_u64 v[36:37], v[36:37], 0, v[64:65]
	v_lshl_add_u64 v[150:151], s[42:43], 0, v[32:33]
	v_mov_b32_e32 v64, v65
	v_add_u32_e32 v32, 0, v35
	v_add_u32_e32 v180, v49, v112
	v_add_u32_e32 v181, v50, v113
	v_add_u32_e32 v182, v49, v114
	v_add_u32_e32 v183, v50, v115
	v_add_u32_e32 v184, v49, v116
	v_add_u32_e32 v185, v50, v117
	v_add_u32_e32 v186, v49, v118
	v_add_u32_e32 v187, v50, v119
	v_add_u32_e32 v188, v49, v121
	v_add_u32_e32 v189, v50, v122
	v_add_u32_e32 v190, v49, v124
	v_add_u32_e32 v191, v50, v125
	v_add_u32_e32 v192, v49, v127
	v_add_u32_e32 v213, v51, v120
	v_add_u32_e32 v214, v51, v123
	v_add_u32_e32 v215, v51, v126
	v_mov_b64_e32 v[114:115], v[66:67]
	v_mov_b64_e32 v[118:119], v[66:67]
	v_mov_b64_e32 v[122:123], v[66:67]
	v_mov_b64_e32 v[126:127], v[66:67]
	s_mov_b32 s78, 0
	v_mov_b32_e32 v156, 0xff800000
	v_mul_f32_e32 v159, 0xc138aa3b, v6
	v_cmp_eq_u32_e32 vcc, 0, v18
	v_mul_lo_u32 v164, v140, s87
	v_ashrrev_i32_e32 v141, 31, v140
	v_mul_lo_u32 v152, v138, s87
	v_ashrrev_i32_e32 v139, 31, v138
	v_mov_b32_e32 v1, v0
	v_mov_b32_e32 v2, v0
	v_mov_b32_e32 v3, v0
	v_mov_b32_e32 v4, v0
	v_mov_b32_e32 v5, v0
	v_mov_b32_e32 v6, v0
	v_mov_b32_e32 v7, v0
	v_mov_b32_e32 v8, v0
	v_mov_b32_e32 v9, v0
	v_mov_b32_e32 v10, v0
	v_mov_b32_e32 v11, v0
	v_mov_b32_e32 v12, v0
	v_mov_b32_e32 v13, v0
	v_mov_b32_e32 v14, v0
	v_mov_b32_e32 v15, v0
	v_mov_b32_e32 v17, v16
	v_mov_b32_e32 v18, v16
	v_mov_b32_e32 v19, v16
	v_mov_b32_e32 v20, v16
	v_mov_b32_e32 v21, v16
	v_mov_b32_e32 v22, v16
	v_mov_b32_e32 v23, v16
	v_mov_b32_e32 v24, v16
	v_mov_b32_e32 v25, v16
	v_mov_b32_e32 v26, v16
	v_mov_b32_e32 v27, v16
	v_mov_b32_e32 v28, v16
	v_mov_b32_e32 v29, v16
	v_mov_b32_e32 v30, v16
	v_mov_b32_e32 v31, v16
	v_lshl_add_u64 v[142:143], s[42:43], 0, v[36:37]
	s_movk_i32 s28, 0x100
	v_mov_b32_e32 v222, 0
	s_mov_b64 s[44:45], 0
	s_movk_i32 s25, 0x700
	v_add_u32_e32 v165, 0x15c00, v32
	v_add_u32_e32 v166, v44, v52
	v_add_u32_e32 v168, v45, v53
	v_add_u32_e32 v169, v45, v54
	v_add_u32_e32 v170, v45, v55
	v_add_u32_e32 v171, v45, v56
	v_add_u32_e32 v172, v47, v46
	v_add_u32_e32 v173, v48, v46
	v_add_u32_e32 v174, v49, v57
	v_add_u32_e32 v175, v50, v58
	v_add_u32_e32 v176, v49, v59
	v_add_u32_e32 v177, v50, v60
	v_add_u32_e32 v178, v49, v61
	v_add_u32_e32 v179, v50, v62
	v_add_u32_e32 v193, v50, v128
	v_add_u32_e32 v194, v49, v130
	v_add_u32_e32 v195, v50, v131
	v_add_u32_e32 v196, v49, v133
	v_add_u32_e32 v197, v50, v134
	v_add_u32_e32 v198, v49, v146
	v_add_u32_e32 v199, v50, v147
	v_add_u32_e32 v200, v49, v148
	v_add_u32_e32 v201, v50, v149
	v_add_u32_e32 v202, v49, v162
	v_add_u32_e32 v203, v50, v163
	v_add_u32_e32 v204, v49, v204
	v_add_u32_e32 v205, v50, v205
	v_add_u32_e32 v206, v51, v206
	v_add_u32_e32 v207, v51, v207
	v_add_u32_e32 v208, v51, v208
	v_add_u32_e32 v209, v51, v63
	v_add_u32_e32 v210, v51, v210
	v_add_u32_e32 v211, v51, v211
	v_add_u32_e32 v212, v51, v212
	v_add_u32_e32 v216, v51, v129
	v_add_u32_e32 v217, v51, v132
	v_add_u32_e32 v218, v51, v135
	v_add_u32_e32 v219, v51, v219
	v_add_u32_e32 v220, v51, v220
	v_add_u32_e32 v221, v51, v221
	v_mov_b64_e32 v[112:113], v[64:65]
	v_mov_b64_e32 v[116:117], v[64:65]
	v_mov_b64_e32 v[120:121], v[64:65]
	v_mov_b64_e32 v[124:125], v[64:65]
	s_mov_b32 s46, 0
	s_mov_b32 s29, 0
	v_lshrrev_b32_e32 v32, 8, v167
	v_mul_u32_u24_e32 v33, 0x3600, v32
	v_add_u32_e32 v168, v168, v33
	v_add_u32_e32 v169, v169, v33
	v_add_u32_e32 v170, v170, v33
	v_add_u32_e32 v171, v171, v33
	v_add_u32_e32 v169, 0xffffee00, v169
	v_add_u32_e32 v170, 0xffffdc00, v170
	v_add_u32_e32 v171, 0xffffca00, v171
	v_mul_u32_u24_e32 v66, 0x60000, v32
	v_mov_b32_e32 v67, 0
	v_lshl_add_u64 v[142:143], v[66:67], 0, v[142:143]
	v_lshl_add_u64 v[252:253], v[66:67], 0, v[252:253]
	v_lshl_add_u64 v[154:155], v[66:67], 0, v[154:155]
	v_lshl_add_u64 v[150:151], v[66:67], 0, v[150:151]
	s_mov_b32 s19, -1
	s_mov_b32 s18, 0xfffe0000
	v_lshl_add_u64 v[252:253], v[252:253], 0, s[18:19]
	s_mov_b32 s18, 0xfffc0000
	v_lshl_add_u64 v[154:155], v[154:155], 0, s[18:19]
	s_mov_b32 s18, 0xfffa0000
	v_lshl_add_u64 v[150:151], v[150:151], 0, s[18:19]
	v_mul_u32_u24_e32 v33, 0x1400, v32
	v_add_u32_e32 v164, v164, v33
	v_add_u32_e32 v152, v152, v33
	v_add_u32_e32 v152, 0xffffec00, v152
	v_lshlrev_b32_e32 v33, 6, v32
	v_add_u32_e32 v140, v140, v33
	v_add_u32_e32 v138, v138, v33
	v_add_u32_e32 v138, 0xffffffc0, v138
	v_lshrrev_b32_e32 v33, 6, v167
	s_nop 1
	v_readfirstlane_b32 s18, v33
	s_lshl_b32 s19, s18, 6
	s_sub_i32 s19, s19, 0xe0
	s_mul_i32 s20, s19, 0x110
	v_add_u32_e32 v172, s20, v172
	v_add_u32_e32 v174, s20, v174
	v_add_u32_e32 v176, s20, v176
	v_add_u32_e32 v178, s20, v178
	v_add_u32_e32 v180, s20, v180
	v_add_u32_e32 v182, s20, v182
	v_add_u32_e32 v184, s20, v184
	v_add_u32_e32 v186, s20, v186
	v_add_u32_e32 v188, s20, v188
	v_add_u32_e32 v190, s20, v190
	v_add_u32_e32 v192, s20, v192
	v_add_u32_e32 v194, s20, v194
	v_add_u32_e32 v196, s20, v196
	v_add_u32_e32 v198, s20, v198
	v_add_u32_e32 v200, s20, v200
; #define LAS __attribute__((address_space(3)))
; template <int dir>
; __device__ __forceinline__ void lru_pass(LAS unsigned char* lds, const Params& P, int b, int h, int q, bool dry) {
;     ...
;         for (int sc = 0; sc < 9; ++sc) {
;             const bool isctx = (sc == 0);
;             const int t0 = cur.t0;
; #pragma unroll
;             for (int j = 0; j < 11; ++j) { if (j != 0 && j < 9) continue;
;                 const int t = t0 + tr * 8 - 1 + j; if (t < 0 || t >= cur.L) rows[j] = (u32x4){0u, 0u, 0u, 0u}; }
;             f32x2 cw2[4][4], cb2[4];
; #pragma unroll
;             for (int k = 0; k < 5; ++k) { const f32x4 a = *(const LAS f32x4*)(CWL + k * 128 + cgp * 8), c2 = *(const LAS f32x4*)(CWL + k * 128 + cgp * 8 + 4);
;                 if (k < 4) { cw2[k][0] = (f32x2){a[0], a[1]}; cw2[k][1] = (f32x2){a[2], a[3]}; cw2[k][2] = (f32x2){c2[0], c2[1]}; cw2[k][3] = (f32x2){c2[2], c2[3]}; }
;                 else { cb2[0] = (f32x2){a[0], a[1]}; cb2[1] = (f32x2){a[2], a[3]}; cb2[2] = (f32x2){c2[0], c2[1]}; cb2[3] = (f32x2){c2[2], c2[3]}; } }
;     ...
;             for (int i = 0; i < NIN; ++i) { const int id = tid + i * NTHREADS;
;                 if (dir == 0) *(LAS u32x4*)(TIN + (id >> 2) * IO_NP + (id & 3) * 16) = inr[i];
;                 else *(LAS u32x4*)(TIN + (id >> 3) * IO_WP + (id & 7) * 16) = inr[i]; }
;             LruTile nxt = cur;
;             if (sc < 8) { nxt = lru_tile(Z, ZC, b, h, dir, sc + 1); lru_load_rows(rows, nxt, tr, cgp);
; #pragma unroll
;                 for (int i = 0; i < NIN; ++i) { const int id = tid + i * NTHREADS;
;                     if (dir == 0) inr[i] = *(const u32x4*)(Zg + (size_t)(nxt.t0 + (id >> 2)) * 128 + (id & 3) * 8);
;                     else inr[i] = *(const u32x4*)(Hg + (size_t)(nxt.t0 + (id >> 3)) * DM + (id & 7) * 4); } }
	v_add_u32_e32 v202, s20, v202
	v_add_u32_e32 v204, s20, v204
	s_mul_i32 s20, s19, 0x90
	v_add_u32_e32 v175, s20, v175
	v_add_u32_e32 v177, s20, v177
	v_add_u32_e32 v179, s20, v179
	v_add_u32_e32 v181, s20, v181
	v_add_u32_e32 v183, s20, v183
	v_add_u32_e32 v185, s20, v185
	v_add_u32_e32 v187, s20, v187
	v_add_u32_e32 v189, s20, v189
	v_add_u32_e32 v191, s20, v191
	v_add_u32_e32 v193, s20, v193
	v_add_u32_e32 v195, s20, v195
	v_add_u32_e32 v197, s20, v197
	v_add_u32_e32 v199, s20, v199
	v_add_u32_e32 v201, s20, v201
	v_add_u32_e32 v203, s20, v203
	v_add_u32_e32 v205, s20, v205
	s_mul_i32 s20, s19, 0x50
	v_add_u32_e32 v206, s20, v206
	v_add_u32_e32 v207, s20, v207
	v_add_u32_e32 v208, s20, v208
	v_add_u32_e32 v209, s20, v209
	v_add_u32_e32 v210, s20, v210
	v_add_u32_e32 v211, s20, v211
	v_add_u32_e32 v212, s20, v212
	v_add_u32_e32 v213, s20, v213
	v_add_u32_e32 v214, s20, v214
	v_add_u32_e32 v215, s20, v215
	v_add_u32_e32 v216, s20, v216
	v_add_u32_e32 v217, s20, v217
	v_add_u32_e32 v218, s20, v218
	v_add_u32_e32 v219, s20, v219
	v_add_u32_e32 v220, s20, v220
	v_add_u32_e32 v221, s20, v221
	s_lshl_b32 s20, s18, 1
	s_sub_i32 s20, 7, s20
	s_lshl_b32 s20, s20, 8
	v_add_u32_e32 v254, s20, v254
	s_sub_i32 s18, 7, s18
	s_lshr_b32 s101, s18, 2
	s_or_b32 s19, s18, 4
	s_cmp_eq_u32 s19, 7
	s_cselect_b64 s[0:1], -1, 0
	s_cmp_eq_u32 s19, 6
	s_cselect_b64 s[16:17], -1, 0
	s_cmp_eq_u32 s19, 5
	s_cselect_b64 s[4:5], -1, 0
	s_cmp_eq_u32 s19, 4
	s_cselect_b64 s[8:9], -1, 0
	s_cmp_eq_u32 s19, 3
	s_cselect_b64 s[10:11], -1, 0
	s_cmp_eq_u32 s19, 2
	s_cselect_b64 s[12:13], -1, 0
	s_cmp_eq_u32 s19, 1
	s_cselect_b64 s[14:15], -1, 0
	s_mov_b32 s98, 0
	s_cmp_eq_u32 s101, 0
	s_cselect_b32 s99, 0x14400, 0
	s_cselect_b32 s100, 0, 0x400
	v_add_u32_e32 v33, 0x14000, v254
	v_mov_b32_e32 v66, 1.0
	v_mov_b32_e32 v67, 0
	ds_write2_b32 v33, v66, v67 offset1:32
	v_lshrrev_b32_e32 v66, 8, v167
	v_lshlrev_b32_e32 v66, 7, v66
	v_bfe_u32 v67, v167, 2, 6
	v_add_u32_e32 v66, v66, v67
	v_and_b32_e32 v67, 3, v167
	v_lshlrev_b32_e32 v67, 4, v67
	v_mul_u32_u24_e32 v168, 0x90, v66
	v_lshl_add_u32 v168, v67, 1, v168
	v_add_u32_e32 v168, s95, v168
	v_add_u32_e32 v169, 0x2400, v168
	v_lshl_add_u32 v66, v66, 8, v67
	v_mov_b32_e32 v67, 0
	s_lshr_b32 s18, s2, 5
	s_add_i32 s18, s18, 8
	s_lshl_b32 s18, s18, 22
	s_add_u32 s18, s18, 0x5470000
	s_and_b32 s19, s2, 7
	s_lshl_b32 s19, s19, 19
	s_add_u32 s18, s18, s19
	s_bfe_u32 s19, s2, 0x20003
	s_lshl_b32 s19, s19, 6
	s_add_u32 s18, s18, s19
	s_add_u32 s18, s22, s18
	s_addc_u32 s19, s23, 0
	v_lshl_add_u64 v[142:143], s[18:19], 0, v[66:67]
	s_mov_b32 s20, 0x4000
	s_mov_b32 s21, 0
	v_lshl_add_u64 v[252:253], v[142:143], 0, s[20:21]
	s_mov_b32 s40, 0x6000000
	s_mov_b32 s41, 0
	s_cmp_eq_u32 s101, 0
	s_cbranch_scc1 .Lpp_b_nox
	s_waitcnt lgkmcnt(0)
	s_barrier
.Lpp_b_nox:
.LBB0_306:
	v_add_u32_e32 v32, s29, v160
	v_cmp_lt_i32_e64 s[18:19], -1, v32
	v_cmp_gt_i32_e64 s[20:21], s28, v32
	s_and_b64 s[18:19], s[18:19], s[20:21]
	v_add_u32_e32 v33, 9, v32
	s_waitcnt vmcnt(10)
	v_cndmask_b32_e64 v71, 0, v71, s[18:19]
	v_cndmask_b32_e64 v70, 0, v70, s[18:19]
	v_cndmask_b32_e64 v69, 0, v69, s[18:19]
	v_cndmask_b32_e64 v68, 0, v68, s[18:19]
	v_cmp_lt_i32_e64 s[18:19], -10, v32
	v_cmp_gt_i32_e64 s[20:21], s28, v33
	s_and_b64 s[18:19], s[18:19], s[20:21]
	v_add_u32_e32 v33, 10, v32
	s_waitcnt vmcnt(1)
	v_cndmask_b32_e64 v107, 0, v107, s[18:19]
	v_cndmask_b32_e64 v106, 0, v106, s[18:19]
	v_cndmask_b32_e64 v105, 0, v105, s[18:19]
	v_cndmask_b32_e64 v104, 0, v104, s[18:19]
	v_cmp_lt_i32_e64 s[18:19], -11, v32
	v_cmp_gt_i32_e64 s[20:21], s28, v33
	ds_read_b128 v[60:63], v165
	ds_read_b128 v[52:55], v165 offset:16
	ds_read_b128 v[44:47], v165 offset:528
	ds_read_b128 v[56:59], v165 offset:512
	ds_read_b128 v[40:43], v165 offset:1040
	ds_read_b128 v[48:51], v165 offset:1024
	ds_read_b128 v[128:131], v165 offset:2064
	ds_read_b128 v[132:135], v165 offset:2048
	ds_read_b128 v[32:35], v165 offset:1552
	ds_read_b128 v[36:39], v165 offset:1536
	v_lshlrev_b32_e32 v66, 16, v68
	v_and_b32_e32 v67, 0xffff0000, v68
	v_lshlrev_b32_e32 v148, 16, v70
	v_and_b32_e32 v149, 0xffff0000, v70
	s_waitcnt lgkmcnt(2)
	v_pk_fma_f32 v[66:67], v[60:61], v[66:67], v[132:133]
	v_lshlrev_b32_e32 v146, 16, v69
	v_and_b32_e32 v147, 0xffff0000, v69
	v_pk_fma_f32 v[148:149], v[52:53], v[148:149], v[128:129]
	v_lshlrev_b32_e32 v224, 16, v71
	v_and_b32_e32 v225, 0xffff0000, v71
	v_lshlrev_b32_e32 v228, 16, v72
	v_and_b32_e32 v229, 0xffff0000, v72
	v_lshlrev_b32_e32 v232, 16, v74
	v_and_b32_e32 v233, 0xffff0000, v74
	v_pk_fma_f32 v[146:147], v[62:63], v[146:147], v[134:135]
	v_pk_fma_f32 v[224:225], v[54:55], v[224:225], v[130:131]
	v_pk_fma_f32 v[66:67], v[56:57], v[228:229], v[66:67]
	v_lshlrev_b32_e32 v230, 16, v73
	v_and_b32_e32 v231, 0xffff0000, v73
	v_pk_fma_f32 v[148:149], v[44:45], v[232:233], v[148:149]
	v_lshlrev_b32_e32 v234, 16, v75
	v_and_b32_e32 v235, 0xffff0000, v75
	v_lshlrev_b32_e32 v236, 16, v76
	v_and_b32_e32 v237, 0xffff0000, v76
	v_lshlrev_b32_e32 v240, 16, v78
	v_and_b32_e32 v241, 0xffff0000, v78
	v_pk_fma_f32 v[146:147], v[58:59], v[230:231], v[146:147]
	v_pk_fma_f32 v[224:225], v[46:47], v[234:235], v[224:225]
	v_pk_fma_f32 v[66:67], v[48:49], v[236:237], v[66:67]
	v_lshlrev_b32_e32 v238, 16, v77
	v_and_b32_e32 v239, 0xffff0000, v77
	v_pk_fma_f32 v[148:149], v[40:41], v[240:241], v[148:149]
	v_lshlrev_b32_e32 v242, 16, v79
	v_and_b32_e32 v243, 0xffff0000, v79
	v_lshlrev_b32_e32 v244, 16, v80
	v_and_b32_e32 v245, 0xffff0000, v80
	v_lshlrev_b32_e32 v248, 16, v82
	v_and_b32_e32 v249, 0xffff0000, v82
	v_pk_fma_f32 v[146:147], v[50:51], v[238:239], v[146:147]
	v_pk_fma_f32 v[224:225], v[42:43], v[242:243], v[224:225]
	s_waitcnt lgkmcnt(0)
; #define LAS __attribute__((address_space(3)))
; __device__ __forceinline__ unsigned cvt_pk_bf16(float lo, float hi) { unsigned r; asm volatile("v_cvt_pk_bf16_f32 %0, %1, %2" : "=v"(r) : "v"(lo), "v"(hi)); return r; }
; __device__ __forceinline__ float bf_lo(unsigned u) { return __uint_as_float(u << 16); }
; __device__ __forceinline__ float bf_hi(unsigned u) { return __uint_as_float(u & 0xffff0000u); }
; template <int dir>
; __device__ __forceinline__ void lru_pass(LAS unsigned char* lds, const Params& P, int b, int h, int q, bool dry) {
;     ...
;             for (int j = 0; j < 8; ++j) {
;                 f32x2 o0 = cb2[0], o1 = cb2[1], o2 = cb2[2], o3 = cb2[3];
; #pragma unroll
;                 for (int k = 0; k < 4; ++k) { const u32x4 rr = rows[j + k];
;                     o0 = cw2[k][0] * (f32x2){bf_lo(rr.x), bf_hi(rr.x)} + o0; o1 = cw2[k][1] * (f32x2){bf_lo(rr.y), bf_hi(rr.y)} + o1;
;                     o2 = cw2[k][2] * (f32x2){bf_lo(rr.z), bf_hi(rr.z)} + o2; o3 = cw2[k][3] * (f32x2){bf_lo(rr.w), bf_hi(rr.w)} + o3; }
;                 u32x4 w; w.x = cvt_pk_bf16(o0[0], o0[1]); w.y = cvt_pk_bf16(o1[0], o1[1]); w.z = cvt_pk_bf16(o2[0], o2[1]); w.w = cvt_pk_bf16(o3[0], o3[1]);
;                 *(LAS u32x4*)(XC + (tr * 8 + j) * XC_PITCH + cgp * 16) = w;
;             }
	v_pk_fma_f32 v[66:67], v[36:37], v[244:245], v[66:67]
	v_lshlrev_b32_e32 v246, 16, v81
	v_and_b32_e32 v247, 0xffff0000, v81
	v_pk_fma_f32 v[148:149], v[32:33], v[248:249], v[148:149]
	v_lshlrev_b32_e32 v250, 16, v83
	v_and_b32_e32 v251, 0xffff0000, v83
	v_pk_fma_f32 v[146:147], v[38:39], v[246:247], v[146:147]
	v_pk_fma_f32 v[162:163], v[34:35], v[250:251], v[224:225]
	v_cvt_pk_bf16_f32 v224, v66, v67
	v_cvt_pk_bf16_f32 v225, v146, v147
	v_cvt_pk_bf16_f32 v226, v148, v149
	v_pk_fma_f32 v[66:67], v[60:61], v[228:229], v[132:133]
	v_pk_fma_f32 v[148:149], v[52:53], v[232:233], v[128:129]
	v_pk_fma_f32 v[146:147], v[62:63], v[230:231], v[134:135]
	v_pk_fma_f32 v[66:67], v[56:57], v[236:237], v[66:67]
	v_pk_fma_f32 v[148:149], v[44:45], v[240:241], v[148:149]
	v_pk_fma_f32 v[146:147], v[58:59], v[238:239], v[146:147]
	v_pk_fma_f32 v[66:67], v[48:49], v[244:245], v[66:67]
	v_pk_fma_f32 v[148:149], v[40:41], v[248:249], v[148:149]
	v_lshlrev_b32_e32 v228, 16, v84
	v_and_b32_e32 v229, 0xffff0000, v84
	v_lshlrev_b32_e32 v232, 16, v86
	v_and_b32_e32 v233, 0xffff0000, v86
	v_cvt_pk_bf16_f32 v227, v162, v163
	v_pk_fma_f32 v[162:163], v[54:55], v[234:235], v[130:131]
	v_pk_fma_f32 v[146:147], v[50:51], v[246:247], v[146:147]
	v_pk_fma_f32 v[66:67], v[36:37], v[228:229], v[66:67]
	v_lshlrev_b32_e32 v230, 16, v85
	v_and_b32_e32 v231, 0xffff0000, v85
	v_pk_fma_f32 v[148:149], v[32:33], v[232:233], v[148:149]
	ds_write_b128 v166, v[224:227]
	v_pk_fma_f32 v[162:163], v[46:47], v[242:243], v[162:163]
	v_pk_fma_f32 v[146:147], v[38:39], v[230:231], v[146:147]
	v_cvt_pk_bf16_f32 v224, v66, v67
	v_pk_fma_f32 v[66:67], v[60:61], v[236:237], v[132:133]
	v_cvt_pk_bf16_f32 v225, v146, v147
	v_cvt_pk_bf16_f32 v226, v148, v149
	v_pk_fma_f32 v[148:149], v[52:53], v[240:241], v[128:129]
	v_pk_fma_f32 v[162:163], v[42:43], v[250:251], v[162:163]
	v_lshlrev_b32_e32 v234, 16, v87
	v_and_b32_e32 v235, 0xffff0000, v87
	v_pk_fma_f32 v[146:147], v[62:63], v[238:239], v[134:135]
	v_pk_fma_f32 v[66:67], v[56:57], v[244:245], v[66:67]
	v_pk_fma_f32 v[148:149], v[44:45], v[248:249], v[148:149]
	v_pk_fma_f32 v[162:163], v[34:35], v[234:235], v[162:163]
	v_pk_fma_f32 v[146:147], v[58:59], v[246:247], v[146:147]
	v_pk_fma_f32 v[66:67], v[48:49], v[228:229], v[66:67]
	v_pk_fma_f32 v[148:149], v[40:41], v[232:233], v[148:149]
	v_lshlrev_b32_e32 v236, 16, v88
	v_and_b32_e32 v237, 0xffff0000, v88
	v_lshlrev_b32_e32 v240, 16, v90
	v_and_b32_e32 v241, 0xffff0000, v90
	v_cvt_pk_bf16_f32 v227, v162, v163
	v_pk_fma_f32 v[162:163], v[54:55], v[242:243], v[130:131]
	v_pk_fma_f32 v[146:147], v[50:51], v[230:231], v[146:147]
	v_pk_fma_f32 v[66:67], v[36:37], v[236:237], v[66:67]
	v_lshlrev_b32_e32 v238, 16, v89
	v_and_b32_e32 v239, 0xffff0000, v89
	v_pk_fma_f32 v[148:149], v[32:33], v[240:241], v[148:149]
	ds_write_b128 v166, v[224:227] offset:272
	v_pk_fma_f32 v[162:163], v[46:47], v[250:251], v[162:163]
	v_pk_fma_f32 v[146:147], v[38:39], v[238:239], v[146:147]
	v_cvt_pk_bf16_f32 v224, v66, v67
	v_pk_fma_f32 v[66:67], v[60:61], v[244:245], v[132:133]
	v_cvt_pk_bf16_f32 v225, v146, v147
	v_cvt_pk_bf16_f32 v226, v148, v149
	v_pk_fma_f32 v[148:149], v[52:53], v[248:249], v[128:129]
	v_pk_fma_f32 v[162:163], v[42:43], v[234:235], v[162:163]
	v_lshlrev_b32_e32 v242, 16, v91
	v_and_b32_e32 v243, 0xffff0000, v91
	v_pk_fma_f32 v[146:147], v[62:63], v[246:247], v[134:135]
	v_pk_fma_f32 v[66:67], v[56:57], v[228:229], v[66:67]
	v_pk_fma_f32 v[148:149], v[44:45], v[232:233], v[148:149]
	v_pk_fma_f32 v[162:163], v[34:35], v[242:243], v[162:163]
	v_pk_fma_f32 v[146:147], v[58:59], v[230:231], v[146:147]
	v_pk_fma_f32 v[66:67], v[48:49], v[236:237], v[66:67]
	v_pk_fma_f32 v[148:149], v[40:41], v[240:241], v[148:149]
	v_lshlrev_b32_e32 v244, 16, v92
	v_and_b32_e32 v245, 0xffff0000, v92
	v_lshlrev_b32_e32 v248, 16, v94
	v_and_b32_e32 v249, 0xffff0000, v94
	v_cvt_pk_bf16_f32 v227, v162, v163
	v_pk_fma_f32 v[162:163], v[54:55], v[250:251], v[130:131]
	v_pk_fma_f32 v[146:147], v[50:51], v[238:239], v[146:147]
	v_pk_fma_f32 v[66:67], v[36:37], v[244:245], v[66:67]
	v_lshlrev_b32_e32 v246, 16, v93
	v_and_b32_e32 v247, 0xffff0000, v93
	v_pk_fma_f32 v[148:149], v[32:33], v[248:249], v[148:149]
	ds_write_b128 v166, v[224:227] offset:544
	v_pk_fma_f32 v[162:163], v[46:47], v[234:235], v[162:163]
	v_pk_fma_f32 v[146:147], v[38:39], v[246:247], v[146:147]
	v_cvt_pk_bf16_f32 v224, v66, v67
	v_pk_fma_f32 v[66:67], v[60:61], v[228:229], v[132:133]
	v_cvt_pk_bf16_f32 v225, v146, v147
	v_cvt_pk_bf16_f32 v226, v148, v149
	v_pk_fma_f32 v[148:149], v[52:53], v[232:233], v[128:129]
	v_pk_fma_f32 v[162:163], v[42:43], v[242:243], v[162:163]
	v_lshlrev_b32_e32 v250, 16, v95
	v_and_b32_e32 v251, 0xffff0000, v95
	v_pk_fma_f32 v[146:147], v[62:63], v[230:231], v[134:135]
	v_pk_fma_f32 v[66:67], v[56:57], v[236:237], v[66:67]
	v_pk_fma_f32 v[148:149], v[44:45], v[240:241], v[148:149]
	v_pk_fma_f32 v[162:163], v[34:35], v[250:251], v[162:163]
	v_pk_fma_f32 v[146:147], v[58:59], v[238:239], v[146:147]
	v_pk_fma_f32 v[66:67], v[48:49], v[244:245], v[66:67]
	v_pk_fma_f32 v[148:149], v[40:41], v[248:249], v[148:149]
	v_lshlrev_b32_e32 v228, 16, v96
	v_and_b32_e32 v229, 0xffff0000, v96
	v_lshlrev_b32_e32 v232, 16, v98
	v_and_b32_e32 v233, 0xffff0000, v98
	v_cvt_pk_bf16_f32 v227, v162, v163
	v_pk_fma_f32 v[162:163], v[54:55], v[234:235], v[130:131]
	v_pk_fma_f32 v[146:147], v[50:51], v[246:247], v[146:147]
	v_pk_fma_f32 v[66:67], v[36:37], v[228:229], v[66:67]
	v_lshlrev_b32_e32 v230, 16, v97
	v_and_b32_e32 v231, 0xffff0000, v97
	v_pk_fma_f32 v[148:149], v[32:33], v[232:233], v[148:149]
	ds_write_b128 v166, v[224:227] offset:816
; #define LAS __attribute__((address_space(3)))
; __device__ __forceinline__ unsigned cvt_pk_bf16(float lo, float hi) { unsigned r; asm volatile("v_cvt_pk_bf16_f32 %0, %1, %2" : "=v"(r) : "v"(lo), "v"(hi)); return r; }
; __device__ __forceinline__ float bf_lo(unsigned u) { return __uint_as_float(u << 16); }
; __device__ __forceinline__ float bf_hi(unsigned u) { return __uint_as_float(u & 0xffff0000u); }
; template <int dir>
; __device__ __forceinline__ void lru_pass(LAS unsigned char* lds, const Params& P, int b, int h, int q, bool dry) {
;     ...
;             for (int j = 0; j < 8; ++j) {
;                 f32x2 o0 = cb2[0], o1 = cb2[1], o2 = cb2[2], o3 = cb2[3];
; #pragma unroll
;                 for (int k = 0; k < 4; ++k) { const u32x4 rr = rows[j + k];
;                     o0 = cw2[k][0] * (f32x2){bf_lo(rr.x), bf_hi(rr.x)} + o0; o1 = cw2[k][1] * (f32x2){bf_lo(rr.y), bf_hi(rr.y)} + o1;
;                     o2 = cw2[k][2] * (f32x2){bf_lo(rr.z), bf_hi(rr.z)} + o2; o3 = cw2[k][3] * (f32x2){bf_lo(rr.w), bf_hi(rr.w)} + o3; }
;                 u32x4 w; w.x = cvt_pk_bf16(o0[0], o0[1]); w.y = cvt_pk_bf16(o1[0], o1[1]); w.z = cvt_pk_bf16(o2[0], o2[1]); w.w = cvt_pk_bf16(o3[0], o3[1]);
;                 *(LAS u32x4*)(XC + (tr * 8 + j) * XC_PITCH + cgp * 16) = w;
;             }
; #pragma unroll
;             for (int i = 0; i < NIN; ++i) { const int id = tid + i * NTHREADS;
;                 if (dir == 0) *(LAS u32x4*)(TIN + (id >> 2) * IO_NP + (id & 3) * 16) = inr[i];
;                 else *(LAS u32x4*)(TIN + (id >> 3) * IO_WP + (id & 7) * 16) = inr[i]; }
;             LruTile nxt = cur;
;             if (sc < 8) { nxt = lru_tile(Z, ZC, b, h, dir, sc + 1); lru_load_rows(rows, nxt, tr, cgp);
; #pragma unroll
;                 for (int i = 0; i < NIN; ++i) { const int id = tid + i * NTHREADS;
;                     if (dir == 0) inr[i] = *(const u32x4*)(Zg + (size_t)(nxt.t0 + (id >> 2)) * 128 + (id & 3) * 8);
;                     else inr[i] = *(const u32x4*)(Hg + (size_t)(nxt.t0 + (id >> 3)) * DM + (id & 7) * 4); } }
	v_pk_fma_f32 v[162:163], v[46:47], v[242:243], v[162:163]
	v_pk_fma_f32 v[146:147], v[38:39], v[230:231], v[146:147]
	v_cvt_pk_bf16_f32 v224, v66, v67
	v_pk_fma_f32 v[66:67], v[60:61], v[236:237], v[132:133]
	v_cvt_pk_bf16_f32 v225, v146, v147
	v_cvt_pk_bf16_f32 v226, v148, v149
	v_pk_fma_f32 v[148:149], v[52:53], v[240:241], v[128:129]
	v_pk_fma_f32 v[162:163], v[42:43], v[250:251], v[162:163]
	v_lshlrev_b32_e32 v234, 16, v99
	v_and_b32_e32 v235, 0xffff0000, v99
	v_pk_fma_f32 v[146:147], v[62:63], v[238:239], v[134:135]
	v_pk_fma_f32 v[66:67], v[56:57], v[244:245], v[66:67]
	v_pk_fma_f32 v[148:149], v[44:45], v[248:249], v[148:149]
	v_pk_fma_f32 v[162:163], v[34:35], v[234:235], v[162:163]
	v_pk_fma_f32 v[146:147], v[58:59], v[246:247], v[146:147]
	v_pk_fma_f32 v[66:67], v[48:49], v[228:229], v[66:67]
	v_pk_fma_f32 v[148:149], v[40:41], v[232:233], v[148:149]
	v_lshlrev_b32_e32 v236, 16, v100
	v_and_b32_e32 v237, 0xffff0000, v100
	v_lshlrev_b32_e32 v240, 16, v102
	v_and_b32_e32 v241, 0xffff0000, v102
	v_cvt_pk_bf16_f32 v227, v162, v163
	v_pk_fma_f32 v[162:163], v[54:55], v[242:243], v[130:131]
	v_pk_fma_f32 v[146:147], v[50:51], v[230:231], v[146:147]
	v_pk_fma_f32 v[66:67], v[36:37], v[236:237], v[66:67]
	v_lshlrev_b32_e32 v238, 16, v101
	v_and_b32_e32 v239, 0xffff0000, v101
	v_pk_fma_f32 v[148:149], v[32:33], v[240:241], v[148:149]
	s_and_b64 s[18:19], s[18:19], s[20:21]
	ds_write_b128 v166, v[224:227] offset:1088
	v_pk_fma_f32 v[162:163], v[46:47], v[250:251], v[162:163]
	v_pk_fma_f32 v[146:147], v[38:39], v[238:239], v[146:147]
	v_cvt_pk_bf16_f32 v224, v66, v67
	v_pk_fma_f32 v[66:67], v[60:61], v[244:245], v[132:133]
	v_cvt_pk_bf16_f32 v225, v146, v147
	v_cvt_pk_bf16_f32 v226, v148, v149
	v_pk_fma_f32 v[148:149], v[52:53], v[248:249], v[128:129]
	v_pk_fma_f32 v[60:61], v[60:61], v[228:229], v[132:133]
	v_pk_fma_f32 v[52:53], v[52:53], v[232:233], v[128:129]
	s_waitcnt vmcnt(0)
	v_cndmask_b32_e64 v108, 0, v108, s[18:19]
	v_pk_fma_f32 v[162:163], v[42:43], v[234:235], v[162:163]
	v_lshlrev_b32_e32 v242, 16, v103
	v_and_b32_e32 v243, 0xffff0000, v103
	v_pk_fma_f32 v[146:147], v[62:63], v[246:247], v[134:135]
	v_pk_fma_f32 v[66:67], v[56:57], v[228:229], v[66:67]
	v_pk_fma_f32 v[148:149], v[44:45], v[232:233], v[148:149]
	v_lshlrev_b32_e32 v244, 16, v104
	v_and_b32_e32 v245, 0xffff0000, v104
	v_lshlrev_b32_e32 v248, 16, v106
	v_and_b32_e32 v249, 0xffff0000, v106
	v_pk_fma_f32 v[62:63], v[62:63], v[230:231], v[134:135]
	v_pk_fma_f32 v[56:57], v[56:57], v[236:237], v[60:61]
	v_pk_fma_f32 v[44:45], v[44:45], v[240:241], v[52:53]
	v_cndmask_b32_e64 v109, 0, v109, s[18:19]
	v_pk_fma_f32 v[162:163], v[34:35], v[242:243], v[162:163]
	v_pk_fma_f32 v[146:147], v[58:59], v[230:231], v[146:147]
	v_pk_fma_f32 v[66:67], v[48:49], v[236:237], v[66:67]
	v_pk_fma_f32 v[148:149], v[40:41], v[240:241], v[148:149]
	v_lshlrev_b32_e32 v246, 16, v105
	v_and_b32_e32 v247, 0xffff0000, v105
	v_pk_fma_f32 v[58:59], v[58:59], v[238:239], v[62:63]
	v_pk_fma_f32 v[48:49], v[48:49], v[244:245], v[56:57]
	v_pk_fma_f32 v[40:41], v[40:41], v[248:249], v[44:45]
	v_lshlrev_b32_e32 v44, 16, v108
	v_and_b32_e32 v45, 0xffff0000, v108
	v_cndmask_b32_e64 v110, 0, v110, s[18:19]
	v_cvt_pk_bf16_f32 v227, v162, v163
	v_pk_fma_f32 v[162:163], v[54:55], v[250:251], v[130:131]
	v_pk_fma_f32 v[146:147], v[50:51], v[238:239], v[146:147]
	v_pk_fma_f32 v[66:67], v[36:37], v[244:245], v[66:67]
	v_pk_fma_f32 v[54:55], v[54:55], v[234:235], v[130:131]
	v_pk_fma_f32 v[50:51], v[50:51], v[246:247], v[58:59]
	v_pk_fma_f32 v[36:37], v[36:37], v[44:45], v[48:49]
	v_lshlrev_b32_e32 v44, 16, v109
	v_and_b32_e32 v45, 0xffff0000, v109
	v_cndmask_b32_e64 v111, 0, v111, s[18:19]
	v_pk_fma_f32 v[162:163], v[46:47], v[234:235], v[162:163]
	v_pk_fma_f32 v[146:147], v[38:39], v[246:247], v[146:147]
	v_lshlrev_b32_e32 v250, 16, v107
	v_and_b32_e32 v251, 0xffff0000, v107
	v_pk_fma_f32 v[46:47], v[46:47], v[242:243], v[54:55]
	v_pk_fma_f32 v[38:39], v[38:39], v[44:45], v[50:51]
	v_lshlrev_b32_e32 v44, 16, v110
	v_and_b32_e32 v45, 0xffff0000, v110
	v_pk_fma_f32 v[162:163], v[42:43], v[242:243], v[162:163]
	v_pk_fma_f32 v[148:149], v[32:33], v[248:249], v[148:149]
	v_pk_fma_f32 v[42:43], v[42:43], v[250:251], v[46:47]
	v_pk_fma_f32 v[40:41], v[32:33], v[44:45], v[40:41]
	v_lshlrev_b32_e32 v32, 16, v111
	v_and_b32_e32 v33, 0xffff0000, v111
	ds_write_b128 v166, v[224:227] offset:1360
	v_pk_fma_f32 v[162:163], v[34:35], v[250:251], v[162:163]
	v_cvt_pk_bf16_f32 v224, v66, v67
	v_cvt_pk_bf16_f32 v225, v146, v147
	v_cvt_pk_bf16_f32 v226, v148, v149
	v_pk_fma_f32 v[42:43], v[34:35], v[32:33], v[42:43]
	v_cvt_pk_bf16_f32 v227, v162, v163
	ds_write_b128 v166, v[224:227] offset:1632
	v_cvt_pk_bf16_f32 v32, v36, v37
	v_cvt_pk_bf16_f32 v33, v38, v39
	v_cvt_pk_bf16_f32 v34, v40, v41
	v_cvt_pk_bf16_f32 v35, v42, v43
	s_cmp_eq_u32 s44, 0xfff80000
	ds_write_b128 v166, v[32:35] offset:1904
	s_mov_b32 s20, 0x5040100
	s_mov_b32 s21, 0x7060302
	v_perm_b32 v232, v112, v120, s20
	v_perm_b32 v233, v112, v120, s21
	v_perm_b32 v234, v113, v121, s20
	v_perm_b32 v235, v113, v121, s21
	v_perm_b32 v236, v114, v122, s20
	v_perm_b32 v237, v114, v122, s21
	v_perm_b32 v238, v115, v123, s20
	v_perm_b32 v239, v115, v123, s21
	v_perm_b32 v240, v116, v124, s20
	v_perm_b32 v241, v116, v124, s21
	v_perm_b32 v242, v117, v125, s20
	v_perm_b32 v243, v117, v125, s21
	v_perm_b32 v244, v118, v126, s20
	v_perm_b32 v245, v118, v126, s21
	v_perm_b32 v246, v119, v127, s20
	v_perm_b32 v247, v119, v127, s21
	ds_write_b128 v168, v[232:235]
	ds_write_b128 v168, v[236:239] offset:16
	ds_write_b128 v169, v[240:243]
	ds_write_b128 v169, v[244:247] offset:16
	s_cbranch_scc1 .LBB0_308
	global_load_dwordx4 v[68:71], v[144:145], off offset:-1280
	global_load_dwordx4 v[72:75], v[144:145], off offset:-1024
	global_load_dwordx4 v[76:79], v[144:145], off offset:-768
	global_load_dwordx4 v[80:83], v[144:145], off offset:-512
	global_load_dwordx4 v[84:87], v[144:145], off offset:-256
	global_load_dwordx4 v[88:91], v[144:145], off
	global_load_dwordx4 v[92:95], v[144:145], off offset:256
	global_load_dwordx4 v[96:99], v[144:145], off offset:512
	global_load_dwordx4 v[100:103], v[144:145], off offset:768
	global_load_dwordx4 v[104:107], v[144:145], off offset:1024
	global_load_dwordx4 v[108:111], v[144:145], off offset:1280
	v_lshl_add_u64 v[32:33], v[142:143], 0, s[44:45]
	v_lshl_add_u64 v[34:35], v[252:253], 0, s[44:45]
	global_load_dwordx4 v[112:115], v[32:33], off
	global_load_dwordx4 v[116:119], v[34:35], off
	v_lshl_add_u64 v[32:33], v[32:33], 0, s[40:41]
	v_lshl_add_u64 v[34:35], v[34:35], 0, s[40:41]
	global_load_dwordx4 v[120:123], v[32:33], off sc1
	global_load_dwordx4 v[124:127], v[34:35], off sc1
	s_movk_i32 s28, 0x800
	s_mov_b32 s20, s25
	s_branch .LBB0_309

; #define LAS __attribute__((address_space(3)))
; __device__ __forceinline__ unsigned cvt_pk_bf16(float lo, float hi) { unsigned r; asm volatile("v_cvt_pk_bf16_f32 %0, %1, %2" : "=v"(r) : "v"(lo), "v"(hi)); return r; }
; __device__ __forceinline__ float bf_lo(unsigned u) { return __uint_as_float(u << 16); }
; __device__ __forceinline__ float bf_hi(unsigned u) { return __uint_as_float(u & 0xffff0000u); }
; __device__ __forceinline__ bf16_t f2bf(float f) { return (bf16_t)(cvt_pk_bf16(f, 0.f) & 0xffffu); }
; template <int dir>
; __device__ __forceinline__ void lru_pass(LAS unsigned char* lds, const Params& P, int b, int h, int q, bool dry) {
;     ...
;         for (int sc = 0; sc < 9; ++sc) {
;     ...
;             float cin = carry, cend = carry;
; #pragma unroll
;             for (int w = 0; w < 8; ++w) { const float pw = AGG[(w * 2 + 0) * 32 + nl], ew = AGG[(w * 2 + 1) * 32 + nl]; if (w == wid) cin = cend; cend = fmaf(pw, cend, ew); }
;             carry = cend;
;             if (g) cin = fmaf(P0, cin, E0);
;             if (!isctx) {
; #pragma unroll
;                 for (int v = 0; v < 16; ++v) { const float hv = fmaf(zi[v], cin, zr[v]);
;                     const int s = sbase + v; const int tl = dir == 0 ? s : 255 - s;
;                     if (dir == 0) *(LAS unsigned*)(TOUT + tl * IO_WP + nl * 4) = (cvt_pk_bf16(hv, 0.f) & 0xffffu) | (pk[v] << 16);
;                     else *(LAS bf16_t*)(TOUT + tl * IO_NP + nl * 2) = f2bf((bf_lo(pk[v]) + hv) * bf_hi(pk[v])); }
;             }
;             t0_prev = t0;
;             cur = nxt;
;         }
.LBB0_315:
	s_xor_b32 s98, s98, 0x14000
	s_xor_b32 s99, s99, 0x14000
	s_xor_b32 s100, s100, 0x14000
	s_add_i32 s46, s46, 1
	s_add_u32 s44, s44, 0xffff0000
	s_mov_b32 s6, 0xffff0000
	s_addc_u32 s45, s45, -1
	s_addk_i32 s25, 0xff00
	s_mov_b32 s7, -1
	s_waitcnt lgkmcnt(0)
	v_fmac_f32_e32 v33, v32, v35
	s_cmp_lg_u32 s46, 9
	v_lshl_add_u64 v[144:145], v[144:145], 0, s[6:7]
	s_cbranch_scc0 .LBB0_277
	v_mov_b32_e32 v222, v33
	s_mov_b32 s78, s29
	s_mov_b32 s29, s20
	s_branch .LBB0_306
